# GEMM K-loops: A-fragment ds_read addresses use one rebased register plus immediate offsets (removes 16 VALU address ops per K-iteration from the load sections)
# speedup vs baseline: 1.0257x; 1.0257x over previous
;   DI void init(f32x4 (&acc)[2][2][4][2], const Unit&, int, int, int, int) const { acc_zero(acc); }
;   DI void init(f32x4 (&acc)[2][2][4][2], const Unit&, int, int, int, int) const { acc_zero(acc); }
; #define PG8_STAGE(bufoff, gbase, voff) do { _Pragma("unroll") for (int _i = 0; _i < 2; ++_i) \
;     __builtin_amdgcn_global_load_lds((const unsigned*)((const char*)(gbase) + (voff)[_i]), (PG8_LAS unsigned*)(lds + (bufoff) + ldsw + _i * 8192), 16, 0, 0); } while (0)
; #define PG8_WAIT_V(n) asm volatile("s_waitcnt vmcnt(" #n ")" ::: "memory")
; #define PG8_BAR __builtin_amdgcn_s_barrier()
; #define PG8_RTAB_LOAD(var, unit) do { if constexpr (Epi::NEEDS_R) { var = *(const uint4*)(E.ssq + (size_t)((unit).pm * BM + (tid >> 1)) * 16 + (tid & 1) * 8); } } while (0)
; template <class Epi>
; DI void gemm_phase(const bf16_t* __restrict__ gA, const bf16_t* __restrict__ gBt, int M, int N, int K, const Epi& E, char* lds_generic) {
;     ...
;   for (int i = 0; i < 2; ++i) { int R, C; stage_rc(tid * 16 + i * 8192, R, C); const int Rb = Epi::PERM ? ((R & ~31) + perm32(R & 31)) : R;
;     voffA[i] = (unsigned)(R * K + C) * 2u; voffB[i] = (unsigned)(Rb * K + C) * 2u; }
;   const size_t kstep = (size_t)(BK * 2);
;   const size_t hstep = (size_t)HALF * K * 2;
;   const size_t tstep = 2 * hstep;
;   const unsigned ldsw = (unsigned)wid * 1024u;
;   const int aoff = lds_byte(wr * 64 + fr, fq * 8), boff = lds_byte(wc * 32 + fr, fq * 8);
;     ...
;   Unit cur, nxt; int ui = 0;
;   if (!S.next(0, cur)) return;
;   f32x4 acc[2][2][4][2];
;   E.init(acc, cur, wr, wc, fr, fq);
;     ...
;   { uint4 rt0_ = {0u, 0u, 0u, 0u}; PG8_RTAB_LOAD(rt0_, cur); PG8_RTAB_FIN(rt0_, 0); }
;   bf16x8 At[4][2], B0[2][2], B1[2][2];
;   const char* cA = (const char*)gA + (size_t)cur.pm * tstep; const char* cB = (const char*)gBt + (size_t)cur.pn * tstep;
;   PG8_STAGE(PG8_SB(0, 0), cB, voffB); PG8_STAGE(PG8_SA(0, 0), cA, voffA); PG8_STAGE(PG8_SB(0, 1), cB + hstep, voffB); PG8_STAGE(PG8_SA(0, 1), cA + hstep, voffA);
;   if (wr == 1) PG8_BAR;
;   PG8_WAIT_V(4); PG8_BAR;
;   PG8_STAGE(PG8_SB(1, 0), cB + kstep, voffB); PG8_STAGE(PG8_SA(1, 0), cA + kstep, voffA); PG8_STAGE(PG8_SB(1, 1), cB + hstep + kstep, voffB);
;   PG8_WAIT_V(6); PG8_BAR;
.LBB0_153:
	v_and_b32_e32 v18, 15, v2
	v_lshrrev_b32_e32 v2, 1, v2
	v_and_b32_e32 v2, 24, v2
	v_lshlrev_b32_e32 v19, 1, v2
	v_lshl_or_b32 v153, s0, 6, v18
	v_lshl_or_b32 v19, v18, 6, v19
	v_lshlrev_b32_e32 v18, 2, v18
	s_lshl_b32 s1, s1, 5
	v_readlane_b32 s28, v255, 9
	s_lshl_b32 s15, s0, 13
	v_and_b32_e32 v20, 32, v18
	s_and_b32 s1, s1, 0x60
	v_readlane_b32 s29, v255, 10
	v_bitop3_b32 v154, v19, s15, v20 bitop3:0xde
	s_lshl_b32 s15, s1, 7
	v_lshl_add_u64 v[10:11], s[28:29], 0, v[0:1]
	v_mov_b32_e32 v139, v1
	v_readlane_b32 s30, v255, 5
	v_bitop3_b32 v155, v19, s15, v20 bitop3:0xde
	v_add_u32_e32 v155, 0x10000, v155
	s_add_i32 s15, s5, 0x18000
	v_lshl_add_u64 v[12:13], s[28:29], 0, v[138:139]
	v_mov_b32_e32 v135, v1
	v_readlane_b32 s31, v255, 6
	v_lshl_add_u64 v[10:11], v[10:11], 0, s[10:11]
	s_mov_b32 m0, s15
	s_add_i32 s16, s5, 0x1a000
	v_lshl_add_u64 v[14:15], s[30:31], 0, v[134:135]
	v_mov_b32_e32 v137, v1
	global_load_lds_dwordx4 v[10:11], off
	v_lshl_add_u64 v[10:11], v[12:13], 0, s[10:11]
	s_mov_b32 m0, s16
	s_add_i32 s18, s5, 0x8000
	v_lshl_add_u64 v[16:17], s[30:31], 0, v[136:137]
	global_load_lds_dwordx4 v[10:11], off
	v_lshl_add_u64 v[10:11], v[14:15], 0, s[10:11]
	s_mov_b32 m0, s18
	s_add_i32 s19, s5, 0xa000
	v_readlane_b32 s22, v255, 11
	global_load_lds_dwordx4 v[10:11], off
	v_lshl_add_u64 v[10:11], v[16:17], 0, s[10:11]
	s_mov_b32 m0, s19
	s_add_i32 s20, s5, 0x1c000
	v_readlane_b32 s23, v255, 12
	global_load_lds_dwordx4 v[10:11], off
	s_nop 0
	v_lshl_add_u64 v[10:11], s[22:23], 0, v[0:1]
	s_mov_b32 m0, s20
	s_add_i32 s21, s5, 0x1e000
	global_load_lds_dwordx4 v[10:11], off
	v_lshl_add_u64 v[10:11], s[22:23], 0, v[138:139]
	s_mov_b32 m0, s21
	v_or_b32_e32 v157, s1, v2
	global_load_lds_dwordx4 v[10:11], off
	s_waitcnt vmcnt(10)
	s_barrier
	v_lshlrev_b32_e32 v2, 14, v3
	v_and_b32_e32 v2, 0xffff8000, v2
	v_lshl_add_u32 v2, v4, 11, v2
	v_and_b32_e32 v3, 1, v3
	v_lshl_or_b32 v2, v3, 6, v2
	v_lshl_add_u32 v142, v5, 1, v2
	v_lshlrev_b32_e32 v2, 14, v7
	s_lshl_b32 s0, s0, 8
	v_and_b32_e32 v2, 0xffff8000, v2
	v_lshlrev_b32_e32 v6, 3, v6
	s_waitcnt vmcnt(6)
	s_add_i32 s0, s0, 0x20040
	v_lshl_add_u32 v2, v8, 11, v2
	v_and_b32_e32 v3, 1, v7
	v_or_b32_e32 v156, s0, v18
	v_lshlrev_b32_e32 v10, 1, v6
	v_mov_b32_e32 v11, v1
	v_lshl_or_b32 v2, v3, 6, v2
	v_readlane_b32 s0, v254, 63
	v_lshl_add_u64 v[140:141], s[70:71], 0, v[10:11]
	v_mov_b32_e32 v143, v1
	v_lshl_add_u32 v144, v9, 1, v2
	v_mov_b32_e32 v145, v1
	s_mov_b32 s42, 0
	v_readlane_b32 s35, v255, 32
	s_mov_b32 s53, s0
	s_barrier
	v_readlane_b32 s1, v255, 0
	s_branch .LBB0_156

; #define PG8_STAGE(bufoff, gbase, voff) do { _Pragma("unroll") for (int _i = 0; _i < 2; ++_i) \
;     __builtin_amdgcn_global_load_lds((const unsigned*)((const char*)(gbase) + (voff)[_i]), (PG8_LAS unsigned*)(lds + (bufoff) + ldsw + _i * 8192), 16, 0, 0); } while (0)
; #define PG8_LDA(dst, b, h) do { _Pragma("unroll") for (int m = 0; m < 4; ++m) _Pragma("unroll") for (int k = 0; k < 2; ++k) dst[m][k] = *(const PG8_LAS bf16x8*)(lds + PG8_SA(b, h) + aoff + m * 2048 + k * 1024); } while (0)
; #define PG8_LDB(dst, b, h) do { _Pragma("unroll") for (int n = 0; n < 2; ++n) _Pragma("unroll") for (int k = 0; k < 2; ++k) dst[n][k] = *(const PG8_LAS bf16x8*)(lds + PG8_SB(b, h) + boff + n * 2048 + k * 1024); } while (0)
; #define PG8_MMA(ai, bj, At, Bt) do { __builtin_amdgcn_s_setprio(1); _Pragma("unroll") for (int m = 0; m < 4; ++m) _Pragma("unroll") for (int n = 0; n < 2; ++n) _Pragma("unroll") for (int k = 0; k < 2; ++k) \
;     acc[ai][bj][m][n] = __builtin_amdgcn_mfma_f32_16x16x32_bf16(Bt[n][k], At[m][k], acc[ai][bj][m][n], 0, 0, 0); __builtin_amdgcn_s_setprio(0); } while (0)
; #define PG8_WAIT_V(n) asm volatile("s_waitcnt vmcnt(" #n ")" ::: "memory")
; #define PG8_WAIT_L(n) asm volatile("s_waitcnt lgkmcnt(" #n ")" ::: "memory")
; #define PG8_BAR __builtin_amdgcn_s_barrier()
; #define PG8_SCHED __builtin_amdgcn_sched_barrier(0)
; template <class Epi>
; DI void gemm_phase(const bf16_t* __restrict__ gA, const bf16_t* __restrict__ gBt, int M, int N, int K, const Epi& E, char* lds_generic) {
;     ...
;       const bool last = (t == nt - 2);
;       const char* a1 = cA + (size_t)(t + 1) * kstep;
;       const char* a2 = last ? nA : cA + (size_t)(t + 2) * kstep; const char* b2 = last ? nB : cB + (size_t)(t + 2) * kstep;
;       const char* a3 = a2 + kstep; const char* b3 = b2 + kstep;
;       PG8_LDB(B0, 0, 0); PG8_SCHED; PG8_LDA(At, 0, 0); PG8_STAGE(PG8_SA(1, 1), a1 + hstep, voffA);
;       PG8_WAIT_L(8); PG8_BAR; PG8_WAIT_L(0); PG8_MMA(0, 0, At, B0); PG8_BAR; PG8_SCHED;
;       PG8_LDB(B1, 0, 1); PG8_STAGE(PG8_SB(0, 0), b2, voffB);
;       PG8_BAR; PG8_WAIT_L(0); PG8_MMA(0, 1, At, B1); PG8_BAR;
;       PG8_LDA(At, 0, 1); PG8_STAGE(PG8_SA(0, 0), a2, voffA);
;       PG8_BAR; PG8_WAIT_L(0); PG8_MMA(1, 0, At, B0); PG8_BAR; PG8_SCHED;
;       PG8_STAGE(PG8_SB(0, 1), b2 + hstep, voffB);
;       PG8_WAIT_V(6); PG8_BAR; PG8_MMA(1, 1, At, B1); PG8_BAR;
.LBB0_159:
	ds_read_b128 v[130:133], v155
	ds_read_b128 v[146:149], v155 offset:1024
	ds_read_b128 v[158:161], v155 offset:2048
	ds_read_b128 v[166:169], v155 offset:3072
	s_add_u32 s23, s80, 0xfffc0080
	s_addc_u32 s24, s81, -1
	s_cmp_eq_u32 s22, 12
	s_cselect_b32 s31, s27, s24
	s_cselect_b32 s30, s58, s23
	s_cselect_b32 s29, s1, s61
	s_cselect_b32 s28, s59, s60
	s_add_i32 m0, s5, 0xc000
	ds_read_b128 v[170:173], v154
	ds_read_b128 v[174:177], v154 offset:1024
	ds_read_b128 v[178:181], v154 offset:2048
	ds_read_b128 v[182:185], v154 offset:3072
	ds_read_b128 v[186:189], v154 offset:4096
	ds_read_b128 v[190:193], v154 offset:5120
	ds_read_b128 v[194:197], v154 offset:6144
	ds_read_b128 v[198:201], v154 offset:7168
	global_load_lds_dwordx4 v142, s[80:81]
	s_add_i32 m0, s5, 0xe000
	s_nop 0
	global_load_lds_dwordx4 v144, s[80:81]
	s_barrier
	s_waitcnt lgkmcnt(0)
	s_waitcnt lgkmcnt(0)
	v_mfma_f32_16x16x32_bf16 v[126:129], v[130:133], v[170:173], v[126:129]
	v_mfma_f32_16x16x32_bf16 v[122:125], v[158:161], v[170:173], v[122:125]
	v_mfma_f32_16x16x32_bf16 v[118:121], v[130:133], v[178:181], v[118:121]
	v_mfma_f32_16x16x32_bf16 v[110:113], v[158:161], v[178:181], v[110:113]
	v_mfma_f32_16x16x32_bf16 v[98:101], v[130:133], v[186:189], v[98:101]
	v_mfma_f32_16x16x32_bf16 v[90:93], v[158:161], v[186:189], v[90:93]
	v_mfma_f32_16x16x32_bf16 v[86:89], v[130:133], v[194:197], v[86:89]
	v_mfma_f32_16x16x32_bf16 v[78:81], v[158:161], v[194:197], v[78:81]
	v_mfma_f32_16x16x32_bf16 v[126:129], v[146:149], v[174:177], v[126:129]
	v_mfma_f32_16x16x32_bf16 v[122:125], v[166:169], v[174:177], v[122:125]
	v_mfma_f32_16x16x32_bf16 v[118:121], v[146:149], v[182:185], v[118:121]
	v_mfma_f32_16x16x32_bf16 v[110:113], v[166:169], v[182:185], v[110:113]
	v_mfma_f32_16x16x32_bf16 v[98:101], v[146:149], v[190:193], v[98:101]
	v_mfma_f32_16x16x32_bf16 v[90:93], v[166:169], v[190:193], v[90:93]
	v_mfma_f32_16x16x32_bf16 v[86:89], v[146:149], v[198:201], v[86:89]
	v_mfma_f32_16x16x32_bf16 v[78:81], v[166:169], v[198:201], v[78:81]
	s_barrier
	s_mov_b32 m0, s6
	ds_read_b128 v[202:205], v155 offset:16384
	ds_read_b128 v[206:209], v155 offset:17408
	ds_read_b128 v[210:213], v155 offset:18432
	ds_read_b128 v[214:217], v155 offset:19456
	global_load_lds_dwordx4 v0, s[28:29]
	s_mov_b32 m0, s7
	s_nop 0
	global_load_lds_dwordx4 v138, s[28:29]
	s_barrier
	s_waitcnt lgkmcnt(0)
	s_waitcnt lgkmcnt(0)
	v_mfma_f32_16x16x32_bf16 v[114:117], v[202:205], v[170:173], v[114:117]
	v_mfma_f32_16x16x32_bf16 v[106:109], v[210:213], v[170:173], v[106:109]
	v_mfma_f32_16x16x32_bf16 v[102:105], v[202:205], v[178:181], v[102:105]
	v_mfma_f32_16x16x32_bf16 v[94:97], v[210:213], v[178:181], v[94:97]
	v_mfma_f32_16x16x32_bf16 v[82:85], v[202:205], v[186:189], v[82:85]
	v_mfma_f32_16x16x32_bf16 v[74:77], v[210:213], v[186:189], v[74:77]
	v_mfma_f32_16x16x32_bf16 v[70:73], v[202:205], v[194:197], v[70:73]
	v_mfma_f32_16x16x32_bf16 v[66:69], v[210:213], v[194:197], v[66:69]
	v_mfma_f32_16x16x32_bf16 v[114:117], v[206:209], v[174:177], v[114:117]
	v_mfma_f32_16x16x32_bf16 v[106:109], v[214:217], v[174:177], v[106:109]
	v_mfma_f32_16x16x32_bf16 v[102:105], v[206:209], v[182:185], v[102:105]
	v_mfma_f32_16x16x32_bf16 v[94:97], v[214:217], v[182:185], v[94:97]
	v_mfma_f32_16x16x32_bf16 v[82:85], v[206:209], v[190:193], v[82:85]
	v_mfma_f32_16x16x32_bf16 v[74:77], v[214:217], v[190:193], v[74:77]
	v_mfma_f32_16x16x32_bf16 v[70:73], v[206:209], v[198:201], v[70:73]
	v_mfma_f32_16x16x32_bf16 v[66:69], v[214:217], v[198:201], v[66:69]
	s_mov_b32 m0, s5
	s_barrier
	ds_read_b128 v[170:173], v154 offset:16384
	ds_read_b128 v[174:177], v154 offset:17408
	ds_read_b128 v[178:181], v154 offset:18432
	ds_read_b128 v[182:185], v154 offset:19456
	ds_read_b128 v[186:189], v154 offset:20480
	ds_read_b128 v[190:193], v154 offset:21504
	ds_read_b128 v[194:197], v154 offset:22528
	ds_read_b128 v[198:201], v154 offset:23552
	global_load_lds_dwordx4 v134, s[30:31]
	s_mov_b32 m0, s8
	s_nop 0
	global_load_lds_dwordx4 v136, s[30:31]
	s_barrier
	s_waitcnt lgkmcnt(0)
	s_waitcnt lgkmcnt(0)
	v_mfma_f32_16x16x32_bf16 v[62:65], v[130:133], v[170:173], v[62:65]
	v_mfma_f32_16x16x32_bf16 v[58:61], v[158:161], v[170:173], v[58:61]
	v_mfma_f32_16x16x32_bf16 v[54:57], v[130:133], v[178:181], v[54:57]
	v_mfma_f32_16x16x32_bf16 v[46:49], v[158:161], v[178:181], v[46:49]
	v_mfma_f32_16x16x32_bf16 v[34:37], v[130:133], v[186:189], v[34:37]
	v_mfma_f32_16x16x32_bf16 v[26:29], v[158:161], v[186:189], v[26:29]
	v_mfma_f32_16x16x32_bf16 v[22:25], v[130:133], v[194:197], v[22:25]
	v_mfma_f32_16x16x32_bf16 v[14:17], v[158:161], v[194:197], v[14:17]
	v_mfma_f32_16x16x32_bf16 v[62:65], v[146:149], v[174:177], v[62:65]
	v_mfma_f32_16x16x32_bf16 v[58:61], v[166:169], v[174:177], v[58:61]
	v_mfma_f32_16x16x32_bf16 v[54:57], v[146:149], v[182:185], v[54:57]
	v_mfma_f32_16x16x32_bf16 v[46:49], v[166:169], v[182:185], v[46:49]
	v_mfma_f32_16x16x32_bf16 v[34:37], v[146:149], v[190:193], v[34:37]
	v_mfma_f32_16x16x32_bf16 v[26:29], v[166:169], v[190:193], v[26:29]
	v_mfma_f32_16x16x32_bf16 v[22:25], v[146:149], v[198:201], v[22:25]
	v_mfma_f32_16x16x32_bf16 v[14:17], v[166:169], v[198:201], v[14:17]
	s_barrier
	s_add_u32 s82, s28, 0x40000
	s_addc_u32 s83, s29, 0
	s_mov_b32 m0, s9
	s_nop 0
	global_load_lds_dwordx4 v0, s[82:83]
	s_mov_b32 m0, s12
	s_nop 0
	global_load_lds_dwordx4 v138, s[82:83]
	s_waitcnt vmcnt(6)
	s_barrier
; #define PG8_STAGE(bufoff, gbase, voff) do { _Pragma("unroll") for (int _i = 0; _i < 2; ++_i) \
;     __builtin_amdgcn_global_load_lds((const unsigned*)((const char*)(gbase) + (voff)[_i]), (PG8_LAS unsigned*)(lds + (bufoff) + ldsw + _i * 8192), 16, 0, 0); } while (0)
; #define PG8_LDA(dst, b, h) do { _Pragma("unroll") for (int m = 0; m < 4; ++m) _Pragma("unroll") for (int k = 0; k < 2; ++k) dst[m][k] = *(const PG8_LAS bf16x8*)(lds + PG8_SA(b, h) + aoff + m * 2048 + k * 1024); } while (0)
; #define PG8_LDB(dst, b, h) do { _Pragma("unroll") for (int n = 0; n < 2; ++n) _Pragma("unroll") for (int k = 0; k < 2; ++k) dst[n][k] = *(const PG8_LAS bf16x8*)(lds + PG8_SB(b, h) + boff + n * 2048 + k * 1024); } while (0)
; #define PG8_MMA(ai, bj, At, Bt) do { __builtin_amdgcn_s_setprio(1); _Pragma("unroll") for (int m = 0; m < 4; ++m) _Pragma("unroll") for (int n = 0; n < 2; ++n) _Pragma("unroll") for (int k = 0; k < 2; ++k) \
;     acc[ai][bj][m][n] = __builtin_amdgcn_mfma_f32_16x16x32_bf16(Bt[n][k], At[m][k], acc[ai][bj][m][n], 0, 0, 0); __builtin_amdgcn_s_setprio(0); } while (0)
; #define PG8_WAIT_V(n) asm volatile("s_waitcnt vmcnt(" #n ")" ::: "memory")
; #define PG8_WAIT_L(n) asm volatile("s_waitcnt lgkmcnt(" #n ")" ::: "memory")
; #define PG8_BAR __builtin_amdgcn_s_barrier()
; #define PG8_SCHED __builtin_amdgcn_sched_barrier(0)
; template <class Epi>
; DI void gemm_phase(const bf16_t* __restrict__ gA, const bf16_t* __restrict__ gBt, int M, int N, int K, const Epi& E, char* lds_generic) {
;     ...
;       PG8_WAIT_V(6); PG8_BAR; PG8_MMA(1, 1, At, B1); PG8_BAR;
;       PG8_LDB(B0, 1, 0); PG8_SCHED; PG8_LDA(At, 1, 0); PG8_STAGE(PG8_SA(0, 1), a2 + hstep, voffA);
;       PG8_WAIT_L(8); PG8_BAR; PG8_WAIT_L(0); PG8_MMA(0, 0, At, B0); PG8_BAR; PG8_SCHED;
;       PG8_LDB(B1, 1, 1); PG8_STAGE(PG8_SB(1, 0), b3, voffB);
;       PG8_BAR; PG8_WAIT_L(0); PG8_MMA(0, 1, At, B1); PG8_BAR;
;       PG8_LDA(At, 1, 1); PG8_STAGE(PG8_SA(1, 0), a3, voffA);
	v_mfma_f32_16x16x32_bf16 v[50:53], v[202:205], v[170:173], v[50:53]
	v_mfma_f32_16x16x32_bf16 v[42:45], v[210:213], v[170:173], v[42:45]
	v_mfma_f32_16x16x32_bf16 v[38:41], v[202:205], v[178:181], v[38:41]
	v_mfma_f32_16x16x32_bf16 v[30:33], v[210:213], v[178:181], v[30:33]
	v_mfma_f32_16x16x32_bf16 v[18:21], v[202:205], v[186:189], v[18:21]
	v_mfma_f32_16x16x32_bf16 v[10:13], v[210:213], v[186:189], v[10:13]
	v_mfma_f32_16x16x32_bf16 v[6:9], v[202:205], v[194:197], v[6:9]
	v_mfma_f32_16x16x32_bf16 v[2:5], v[210:213], v[194:197], v[2:5]
	v_mfma_f32_16x16x32_bf16 v[50:53], v[206:209], v[174:177], v[50:53]
	v_mfma_f32_16x16x32_bf16 v[42:45], v[214:217], v[174:177], v[42:45]
	v_mfma_f32_16x16x32_bf16 v[38:41], v[206:209], v[182:185], v[38:41]
	v_mfma_f32_16x16x32_bf16 v[30:33], v[214:217], v[182:185], v[30:33]
	v_mfma_f32_16x16x32_bf16 v[18:21], v[206:209], v[190:193], v[18:21]
	v_mfma_f32_16x16x32_bf16 v[10:13], v[214:217], v[190:193], v[10:13]
	v_mfma_f32_16x16x32_bf16 v[6:9], v[206:209], v[198:201], v[6:9]
	v_mfma_f32_16x16x32_bf16 v[2:5], v[214:217], v[198:201], v[2:5]
	s_barrier
	ds_read_b128 v[130:133], v155 offset:32768
	ds_read_b128 v[146:149], v155 offset:33792
	ds_read_b128 v[158:161], v155 offset:34816
	ds_read_b128 v[166:169], v155 offset:35840
	s_add_u32 s30, s30, 0x40000
	s_addc_u32 s31, s31, 0
	s_mov_b32 m0, s13
	ds_read_b128 v[170:173], v154 offset:32768
	ds_read_b128 v[174:177], v154 offset:33792
	ds_read_b128 v[178:181], v154 offset:34816
	ds_read_b128 v[182:185], v154 offset:35840
	ds_read_b128 v[186:189], v154 offset:36864
	ds_read_b128 v[190:193], v154 offset:37888
	ds_read_b128 v[194:197], v154 offset:38912
	ds_read_b128 v[198:201], v154 offset:39936
	global_load_lds_dwordx4 v134, s[30:31]
	s_mov_b32 m0, s14
	s_nop 0
	global_load_lds_dwordx4 v136, s[30:31]
	s_barrier
	s_waitcnt lgkmcnt(0)
	s_waitcnt lgkmcnt(0)
	v_mfma_f32_16x16x32_bf16 v[126:129], v[130:133], v[170:173], v[126:129]
	v_mfma_f32_16x16x32_bf16 v[122:125], v[158:161], v[170:173], v[122:125]
	v_mfma_f32_16x16x32_bf16 v[118:121], v[130:133], v[178:181], v[118:121]
	v_mfma_f32_16x16x32_bf16 v[110:113], v[158:161], v[178:181], v[110:113]
	v_mfma_f32_16x16x32_bf16 v[98:101], v[130:133], v[186:189], v[98:101]
	v_mfma_f32_16x16x32_bf16 v[90:93], v[158:161], v[186:189], v[90:93]
	v_mfma_f32_16x16x32_bf16 v[86:89], v[130:133], v[194:197], v[86:89]
	v_mfma_f32_16x16x32_bf16 v[78:81], v[158:161], v[194:197], v[78:81]
	v_mfma_f32_16x16x32_bf16 v[126:129], v[146:149], v[174:177], v[126:129]
	v_mfma_f32_16x16x32_bf16 v[122:125], v[166:169], v[174:177], v[122:125]
	v_mfma_f32_16x16x32_bf16 v[118:121], v[146:149], v[182:185], v[118:121]
	v_mfma_f32_16x16x32_bf16 v[110:113], v[166:169], v[182:185], v[110:113]
	v_mfma_f32_16x16x32_bf16 v[98:101], v[146:149], v[190:193], v[98:101]
	v_mfma_f32_16x16x32_bf16 v[90:93], v[166:169], v[190:193], v[90:93]
	v_mfma_f32_16x16x32_bf16 v[86:89], v[146:149], v[198:201], v[86:89]
	v_mfma_f32_16x16x32_bf16 v[78:81], v[166:169], v[198:201], v[78:81]
	s_barrier
	s_mov_b32 m0, s15
	ds_read_b128 v[202:205], v155 offset:49152
	ds_read_b128 v[206:209], v155 offset:50176
	ds_read_b128 v[210:213], v155 offset:51200
	ds_read_b128 v[214:217], v155 offset:52224
	s_add_u32 s82, s28, 0x80
	s_addc_u32 s83, s29, 0
	global_load_lds_dwordx4 v0, s[82:83]
	s_mov_b32 m0, s16
	s_nop 0
	s_add_u32 s82, s28, 0x80
	s_addc_u32 s83, s29, 0
	global_load_lds_dwordx4 v138, s[82:83]
	s_barrier
	s_waitcnt lgkmcnt(0)
	s_waitcnt lgkmcnt(0)
	v_mfma_f32_16x16x32_bf16 v[114:117], v[202:205], v[170:173], v[114:117]
	v_mfma_f32_16x16x32_bf16 v[106:109], v[210:213], v[170:173], v[106:109]
	v_mfma_f32_16x16x32_bf16 v[102:105], v[202:205], v[178:181], v[102:105]
	v_mfma_f32_16x16x32_bf16 v[94:97], v[210:213], v[178:181], v[94:97]
	v_mfma_f32_16x16x32_bf16 v[82:85], v[202:205], v[186:189], v[82:85]
	v_mfma_f32_16x16x32_bf16 v[74:77], v[210:213], v[186:189], v[74:77]
	v_mfma_f32_16x16x32_bf16 v[70:73], v[202:205], v[194:197], v[70:73]
	v_mfma_f32_16x16x32_bf16 v[66:69], v[210:213], v[194:197], v[66:69]
	v_mfma_f32_16x16x32_bf16 v[114:117], v[206:209], v[174:177], v[114:117]
	v_mfma_f32_16x16x32_bf16 v[106:109], v[214:217], v[174:177], v[106:109]
	v_mfma_f32_16x16x32_bf16 v[102:105], v[206:209], v[182:185], v[102:105]
	v_mfma_f32_16x16x32_bf16 v[94:97], v[214:217], v[182:185], v[94:97]
	v_mfma_f32_16x16x32_bf16 v[82:85], v[206:209], v[190:193], v[82:85]
	v_mfma_f32_16x16x32_bf16 v[74:77], v[214:217], v[190:193], v[74:77]
	v_mfma_f32_16x16x32_bf16 v[70:73], v[206:209], v[198:201], v[70:73]
	v_mfma_f32_16x16x32_bf16 v[66:69], v[214:217], v[198:201], v[66:69]
	s_mov_b32 m0, s18
	s_barrier
; #define PG8_STAGE(bufoff, gbase, voff) do { _Pragma("unroll") for (int _i = 0; _i < 2; ++_i) \
;     __builtin_amdgcn_global_load_lds((const unsigned*)((const char*)(gbase) + (voff)[_i]), (PG8_LAS unsigned*)(lds + (bufoff) + ldsw + _i * 8192), 16, 0, 0); } while (0)
; #define PG8_LDA(dst, b, h) do { _Pragma("unroll") for (int m = 0; m < 4; ++m) _Pragma("unroll") for (int k = 0; k < 2; ++k) dst[m][k] = *(const PG8_LAS bf16x8*)(lds + PG8_SA(b, h) + aoff + m * 2048 + k * 1024); } while (0)
; #define PG8_MMA(ai, bj, At, Bt) do { __builtin_amdgcn_s_setprio(1); _Pragma("unroll") for (int m = 0; m < 4; ++m) _Pragma("unroll") for (int n = 0; n < 2; ++n) _Pragma("unroll") for (int k = 0; k < 2; ++k) \
;     acc[ai][bj][m][n] = __builtin_amdgcn_mfma_f32_16x16x32_bf16(Bt[n][k], At[m][k], acc[ai][bj][m][n], 0, 0, 0); __builtin_amdgcn_s_setprio(0); } while (0)
; #define PG8_WAIT_V(n) asm volatile("s_waitcnt vmcnt(" #n ")" ::: "memory")
; #define PG8_WAIT_L(n) asm volatile("s_waitcnt lgkmcnt(" #n ")" ::: "memory")
; #define PG8_BAR __builtin_amdgcn_s_barrier()
; #define PG8_SCHED __builtin_amdgcn_sched_barrier(0)
; #define PG8_RTAB_LOAD(var, unit) do { if constexpr (Epi::NEEDS_R) { var = *(const uint4*)(E.ssq + (size_t)((unit).pm * BM + (tid >> 1)) * 16 + (tid & 1) * 8); } } while (0)
; template <class Epi>
; DI void gemm_phase(const bf16_t* __restrict__ gA, const bf16_t* __restrict__ gBt, int M, int N, int K, const Epi& E, char* lds_generic) {
;     ...
;       PG8_LDA(At, 1, 1); PG8_STAGE(PG8_SA(1, 0), a3, voffA);
;       PG8_BAR; PG8_WAIT_L(0); PG8_MMA(1, 0, At, B0); PG8_BAR; PG8_SCHED;
;       PG8_STAGE(PG8_SB(1, 1), b3 + hstep, voffB);
;       PG8_WAIT_V(6); PG8_BAR; PG8_MMA(1, 1, At, B1); PG8_BAR;
;     }
;     uint4 rtn_ = {0u, 0u, 0u, 0u};
;     if (has_next) PG8_RTAB_LOAD(rtn_, nxt);
	ds_read_b128 v[170:173], v154 offset:49152
	ds_read_b128 v[174:177], v154 offset:50176
	ds_read_b128 v[178:181], v154 offset:51200
	ds_read_b128 v[182:185], v154 offset:52224
	ds_read_b128 v[186:189], v154 offset:53248
	ds_read_b128 v[190:193], v154 offset:54272
	ds_read_b128 v[194:197], v154 offset:55296
	ds_read_b128 v[198:201], v154 offset:56320
	s_add_u32 s82, s30, 0xfffc0080
	s_addc_u32 s83, s31, -1
	global_load_lds_dwordx4 v134, s[82:83]
	s_mov_b32 m0, s19
	s_nop 0
	s_add_u32 s82, s30, 0xfffc0080
	s_addc_u32 s83, s31, -1
	global_load_lds_dwordx4 v136, s[82:83]
	s_barrier
	s_waitcnt lgkmcnt(0)
	s_waitcnt lgkmcnt(0)
	v_mfma_f32_16x16x32_bf16 v[62:65], v[130:133], v[170:173], v[62:65]
	v_mfma_f32_16x16x32_bf16 v[58:61], v[158:161], v[170:173], v[58:61]
	v_mfma_f32_16x16x32_bf16 v[54:57], v[130:133], v[178:181], v[54:57]
	v_mfma_f32_16x16x32_bf16 v[46:49], v[158:161], v[178:181], v[46:49]
	v_mfma_f32_16x16x32_bf16 v[34:37], v[130:133], v[186:189], v[34:37]
	v_mfma_f32_16x16x32_bf16 v[26:29], v[158:161], v[186:189], v[26:29]
	v_mfma_f32_16x16x32_bf16 v[22:25], v[130:133], v[194:197], v[22:25]
	v_mfma_f32_16x16x32_bf16 v[14:17], v[158:161], v[194:197], v[14:17]
	v_mfma_f32_16x16x32_bf16 v[62:65], v[146:149], v[174:177], v[62:65]
	v_mfma_f32_16x16x32_bf16 v[58:61], v[166:169], v[174:177], v[58:61]
	v_mfma_f32_16x16x32_bf16 v[54:57], v[146:149], v[182:185], v[54:57]
	v_mfma_f32_16x16x32_bf16 v[46:49], v[166:169], v[182:185], v[46:49]
	v_mfma_f32_16x16x32_bf16 v[34:37], v[146:149], v[190:193], v[34:37]
	v_mfma_f32_16x16x32_bf16 v[26:29], v[166:169], v[190:193], v[26:29]
	v_mfma_f32_16x16x32_bf16 v[22:25], v[146:149], v[198:201], v[22:25]
	v_mfma_f32_16x16x32_bf16 v[14:17], v[166:169], v[198:201], v[14:17]
	s_barrier
	s_add_u32 s28, s28, 0x40080
	s_addc_u32 s29, s29, 0
	s_mov_b32 m0, s20
	s_nop 0
	global_load_lds_dwordx4 v0, s[28:29]
	s_mov_b32 m0, s21
	s_nop 0
	global_load_lds_dwordx4 v138, s[28:29]
	s_waitcnt vmcnt(6)
	s_barrier
	v_mfma_f32_16x16x32_bf16 v[50:53], v[202:205], v[170:173], v[50:53]
	v_mfma_f32_16x16x32_bf16 v[42:45], v[210:213], v[170:173], v[42:45]
	v_mfma_f32_16x16x32_bf16 v[38:41], v[202:205], v[178:181], v[38:41]
	v_mfma_f32_16x16x32_bf16 v[30:33], v[210:213], v[178:181], v[30:33]
	v_mfma_f32_16x16x32_bf16 v[18:21], v[202:205], v[186:189], v[18:21]
	v_mfma_f32_16x16x32_bf16 v[10:13], v[210:213], v[186:189], v[10:13]
	v_mfma_f32_16x16x32_bf16 v[6:9], v[202:205], v[194:197], v[6:9]
	v_mfma_f32_16x16x32_bf16 v[2:5], v[210:213], v[194:197], v[2:5]
	v_mfma_f32_16x16x32_bf16 v[50:53], v[206:209], v[174:177], v[50:53]
	v_mfma_f32_16x16x32_bf16 v[42:45], v[214:217], v[174:177], v[42:45]
	v_mfma_f32_16x16x32_bf16 v[38:41], v[206:209], v[182:185], v[38:41]
	v_mfma_f32_16x16x32_bf16 v[30:33], v[214:217], v[182:185], v[30:33]
	v_mfma_f32_16x16x32_bf16 v[18:21], v[206:209], v[190:193], v[18:21]
	v_mfma_f32_16x16x32_bf16 v[10:13], v[214:217], v[190:193], v[10:13]
	v_mfma_f32_16x16x32_bf16 v[6:9], v[206:209], v[198:201], v[6:9]
	v_mfma_f32_16x16x32_bf16 v[2:5], v[214:217], v[198:201], v[2:5]
	s_add_i32 s22, s22, 2
	s_add_u32 s80, s80, 0x100
	s_addc_u32 s81, s81, 0
	s_add_u32 s60, s60, 0x100
	s_addc_u32 s61, s61, 0
	s_cmp_gt_u32 s22, 13
	s_barrier
	s_cbranch_scc0 .LBB0_159
	v_mov_b32_e32 v130, 0
	s_and_b64 vcc, exec, s[38:39]
	v_mov_b32_e32 v131, 0
	v_mov_b32_e32 v132, 0
	v_mov_b32_e32 v133, 0
	s_cbranch_vccz .LBB0_162
	v_lshl_add_u32 v130, s26, 8, v150
	v_ashrrev_i32_e32 v131, 31, v130
	v_lshlrev_b64 v[130:131], 5, v[130:131]
	v_lshl_add_u64 v[130:131], v[140:141], 0, v[130:131]
	global_load_dwordx4 v[130:133], v[130:131], off

; DI float bflo(unsigned u) { return __uint_as_float(u << 16); }
; DI float bfhi(unsigned u) { return __uint_as_float(u & 0xffff0000u); }
;   DI void init(f32x4 (&acc)[2][2][4][2], const Unit&, int, int, int, int) const { acc_zero(acc); }
; #define PG8_BAR __builtin_amdgcn_s_barrier()
;   DI void init(f32x4 (&acc)[2][2][4][2], const Unit& u, int wr, int wc, int fr, int fq) const {
;     const int row0 = u.pm * BM + wr * 64 + fr, col0 = u.pn * BM + wc * 32 + 8 * fq; const float ic = 1.f / coef;
; #pragma unroll
;     for (int ai = 0; ai < 2; ++ai)
; #pragma unroll
;       for (int m = 0; m < 4; ++m) { const bf16_t* rowp = src + (size_t)(row0 + ai * HALF + m * 16) * DM + col0;
; #pragma unroll
;         for (int bj = 0; bj < 2; ++bj) { const u32x4 w = *(const u32x4*)(rowp + bj * HALF);
;           acc[ai][bj][m][0] = (f32x4){bflo(w.x), bfhi(w.x), bflo(w.y), bfhi(w.y)} * ic; acc[ai][bj][m][1] = (f32x4){bflo(w.z), bfhi(w.z), bflo(w.w), bfhi(w.w)} * ic; } }
; template <class Epi>
; DI void gemm_phase(const bf16_t* __restrict__ gA, const bf16_t* __restrict__ gBt, int M, int N, int K, const Epi& E, char* lds_generic) {
;     ...
;   for (int i = 0; i < 2; ++i) { int R, C; stage_rc(tid * 16 + i * 8192, R, C); const int Rb = Epi::PERM ? ((R & ~31) + perm32(R & 31)) : R;
;     voffA[i] = (unsigned)(R * K + C) * 2u; voffB[i] = (unsigned)(Rb * K + C) * 2u; }
;   const size_t kstep = (size_t)(BK * 2);
;   const size_t hstep = (size_t)HALF * K * 2;
;   const size_t tstep = 2 * hstep;
;   const unsigned ldsw = (unsigned)wid * 1024u;
;   const int aoff = lds_byte(wr * 64 + fr, fq * 8), boff = lds_byte(wc * 32 + fr, fq * 8);
;     ...
;   Unit cur, nxt; int ui = 0;
;   if (!S.next(0, cur)) return;
;   f32x4 acc[2][2][4][2];
;   E.init(acc, cur, wr, wc, fr, fq);
;     ...
;   { uint4 rt0_ = {0u, 0u, 0u, 0u}; PG8_RTAB_LOAD(rt0_, cur); PG8_RTAB_FIN(rt0_, 0); }
;   bf16x8 At[4][2], B0[2][2], B1[2][2];
;   const char* cA = (const char*)gA + (size_t)cur.pm * tstep; const char* cB = (const char*)gBt + (size_t)cur.pn * tstep;
;   PG8_STAGE(PG8_SB(0, 0), cB, voffB); PG8_STAGE(PG8_SA(0, 0), cA, voffA); PG8_STAGE(PG8_SB(0, 1), cB + hstep, voffB); PG8_STAGE(PG8_SA(0, 1), cA + hstep, voffA);
;   if (wr == 1) PG8_BAR;
;   PG8_WAIT_V(4); PG8_BAR;
;   PG8_STAGE(PG8_SB(1, 0), cB + kstep, voffB); PG8_STAGE(PG8_SA(1, 0), cA + kstep, voffA); PG8_STAGE(PG8_SB(1, 1), cB + hstep + kstep, voffB);
;   PG8_WAIT_V(6); PG8_BAR;
.LBB0_502:
	v_readlane_b32 s22, v254, 45
	v_readlane_b32 s23, v254, 46
	s_waitcnt vmcnt(0)
	v_lshlrev_b32_e32 v102, 16, v42
	v_and_b32_e32 v103, 0xffff0000, v42
	v_lshlrev_b32_e32 v104, 16, v43
	v_and_b32_e32 v105, 0xffff0000, v43
	v_lshlrev_b32_e32 v114, 16, v44
	v_and_b32_e32 v115, 0xffff0000, v44
	v_lshlrev_b32_e32 v116, 16, v45
	v_and_b32_e32 v117, 0xffff0000, v45
	v_lshlrev_b32_e32 v86, 16, v22
	v_and_b32_e32 v87, 0xffff0000, v22
	v_lshlrev_b32_e32 v88, 16, v23
	v_and_b32_e32 v89, 0xffff0000, v23
	v_lshlrev_b32_e32 v98, 16, v24
	v_and_b32_e32 v99, 0xffff0000, v24
	v_lshlrev_b32_e32 v100, 16, v25
	v_and_b32_e32 v101, 0xffff0000, v25
	v_lshlrev_b32_e32 v42, 16, v38
	v_and_b32_e32 v43, 0xffff0000, v38
	v_lshlrev_b32_e32 v44, 16, v39
	v_and_b32_e32 v45, 0xffff0000, v39
	v_lshlrev_b32_e32 v22, 16, v40
	v_and_b32_e32 v23, 0xffff0000, v40
	v_lshlrev_b32_e32 v24, 16, v41
	v_and_b32_e32 v25, 0xffff0000, v41
	v_lshlrev_b32_e32 v38, 16, v46
	v_and_b32_e32 v39, 0xffff0000, v46
	v_lshlrev_b32_e32 v40, 16, v47
	v_and_b32_e32 v41, 0xffff0000, v47
	v_lshl_add_u64 v[46:47], s[22:23], 0, v[0:1]
	v_mov_b32_e32 v131, v1
	v_readlane_b32 s28, v254, 41
	s_add_i32 s8, s6, 0x18000
	v_lshlrev_b32_e32 v90, 16, v58
	v_and_b32_e32 v91, 0xffff0000, v58
	v_lshlrev_b32_e32 v92, 16, v59
	v_and_b32_e32 v93, 0xffff0000, v59
	v_lshlrev_b32_e32 v82, 16, v60
	v_and_b32_e32 v83, 0xffff0000, v60
	v_lshlrev_b32_e32 v84, 16, v61
	v_and_b32_e32 v85, 0xffff0000, v61
	v_lshlrev_b32_e32 v58, 16, v18
	v_and_b32_e32 v59, 0xffff0000, v18
	v_lshlrev_b32_e32 v60, 16, v19
	v_and_b32_e32 v61, 0xffff0000, v19
	v_lshlrev_b32_e32 v74, 16, v20
	v_and_b32_e32 v75, 0xffff0000, v20
	v_lshlrev_b32_e32 v76, 16, v21
	v_and_b32_e32 v77, 0xffff0000, v21
	v_lshlrev_b32_e32 v18, 16, v48
	v_and_b32_e32 v19, 0xffff0000, v48
	v_lshlrev_b32_e32 v20, 16, v49
	v_and_b32_e32 v21, 0xffff0000, v49
	v_lshl_add_u64 v[48:49], s[22:23], 0, v[130:131]
	v_mov_b32_e32 v135, v1
	v_readlane_b32 s29, v254, 42
	v_lshl_add_u64 v[46:47], v[46:47], 0, s[10:11]
	s_mov_b32 m0, s8
	s_add_i32 s9, s6, 0x1a000
	v_lshl_add_u64 v[70:71], s[28:29], 0, v[134:135]
	v_mov_b32_e32 v133, v1
	global_load_lds_dwordx4 v[46:47], off
	v_lshl_add_u64 v[46:47], v[48:49], 0, s[10:11]
	s_mov_b32 m0, s9
	s_add_i32 s19, s6, 0x8000
	v_lshl_add_u64 v[72:73], s[28:29], 0, v[132:133]
	global_load_lds_dwordx4 v[46:47], off
	v_lshl_add_u64 v[46:47], v[70:71], 0, s[10:11]
	s_mov_b32 m0, s19
	s_add_i32 s33, s6, 0xa000
	v_readlane_b32 s24, v254, 47
	global_load_lds_dwordx4 v[46:47], off
	v_lshl_add_u64 v[46:47], v[72:73], 0, s[10:11]
	s_mov_b32 m0, s33
	s_add_i32 s35, s6, 0x1c000
	v_readlane_b32 s25, v254, 48
	global_load_lds_dwordx4 v[46:47], off
	s_nop 0
	v_lshl_add_u64 v[46:47], s[24:25], 0, v[0:1]
	s_mov_b32 m0, s35
	s_add_i32 s42, s6, 0x1e000
	global_load_lds_dwordx4 v[46:47], off
	v_lshl_add_u64 v[46:47], s[24:25], 0, v[130:131]
	s_mov_b32 m0, s42
	v_or_b32_e32 v144, s20, v140
	global_load_lds_dwordx4 v[46:47], off
	s_waitcnt vmcnt(10)
	s_barrier
	v_lshlrev_b32_e32 v145, 6, v144
	v_lshlrev_b32_e32 v146, 4, v136
	s_movk_i32 s20, 0x3c0
	v_lshlrev_b32_e32 v147, 2, v144
	v_and_or_b32 v145, v145, s20, v146
	s_lshl_b32 s1, s1, 13
	v_and_b32_e32 v147, 32, v147
	v_lshl_or_b32 v146, v140, 6, v146
	v_lshlrev_b32_e32 v140, 2, v140
	v_bitop3_b32 v145, v145, s1, v147 bitop3:0xde
	s_lshl_b32 s1, s5, 12
	v_and_b32_e32 v140, 32, v140
	v_bitop3_b32 v146, v146, s1, v140 bitop3:0xde
	v_add_u32_e32 v146, 0x10000, v146
	v_cmp_eq_u32_e64 s[36:37], 0, v136
	v_lshlrev_b32_e32 v136, 14, v143
	v_lshlrev_b32_e32 v140, 14, v138
	v_and_b32_e32 v136, 0xffff8000, v136
	v_and_b32_e32 v140, 0xffff8000, v140
	s_waitcnt vmcnt(6)
	v_or_b32_e32 v147, s0, v137
	v_lshl_add_u32 v136, v142, 11, v136
	v_and_b32_e32 v137, 1, v143
	v_lshl_add_u32 v139, v139, 11, v140
	v_and_b32_e32 v138, 1, v138
	v_readlane_b32 s0, v254, 35
	v_lshl_or_b32 v136, v137, 6, v136
	v_lshl_or_b32 v138, v138, 6, v139
	v_readlane_b32 s1, v254, 36
	v_lshlrev_b32_e32 v118, 16, v62
	v_and_b32_e32 v119, 0xffff0000, v62
	v_lshlrev_b32_e32 v120, 16, v63
	v_and_b32_e32 v121, 0xffff0000, v63
	v_lshlrev_b32_e32 v110, 16, v64
	v_and_b32_e32 v111, 0xffff0000, v64
	v_lshlrev_b32_e32 v112, 16, v65
	v_and_b32_e32 v113, 0xffff0000, v65
	v_lshlrev_b32_e32 v122, 16, v54
	v_and_b32_e32 v123, 0xffff0000, v54
	v_lshlrev_b32_e32 v124, 16, v55
	v_and_b32_e32 v125, 0xffff0000, v55
	v_lshlrev_b32_e32 v126, 16, v56
	v_and_b32_e32 v127, 0xffff0000, v56
	v_lshlrev_b32_e32 v128, 16, v57
	v_and_b32_e32 v129, 0xffff0000, v57
	v_lshlrev_b32_e32 v62, 16, v50
	v_and_b32_e32 v63, 0xffff0000, v50
	v_lshlrev_b32_e32 v64, 16, v51
	v_and_b32_e32 v65, 0xffff0000, v51
	v_lshlrev_b32_e32 v50, 16, v52
	v_and_b32_e32 v51, 0xffff0000, v52
	v_lshlrev_b32_e32 v52, 16, v53
	v_and_b32_e32 v53, 0xffff0000, v53
	v_lshlrev_b32_e32 v54, 16, v10
	v_and_b32_e32 v55, 0xffff0000, v10
	v_lshlrev_b32_e32 v56, 16, v11
	v_and_b32_e32 v57, 0xffff0000, v11
	v_lshlrev_b32_e32 v66, 16, v12
	v_and_b32_e32 v67, 0xffff0000, v12
	v_lshlrev_b32_e32 v68, 16, v13
	v_and_b32_e32 v69, 0xffff0000, v13
	v_lshlrev_b32_e32 v10, 16, v2
	v_and_b32_e32 v11, 0xffff0000, v2
	v_lshlrev_b32_e32 v12, 16, v3
	v_and_b32_e32 v13, 0xffff0000, v3
	v_lshlrev_b32_e32 v2, 16, v4
	v_and_b32_e32 v3, 0xffff0000, v4
	v_lshlrev_b32_e32 v4, 16, v5
	v_and_b32_e32 v5, 0xffff0000, v5
	v_lshlrev_b32_e32 v94, 16, v14
	v_and_b32_e32 v95, 0xffff0000, v14
	v_lshlrev_b32_e32 v96, 16, v15
	v_and_b32_e32 v97, 0xffff0000, v15
	v_lshlrev_b32_e32 v106, 16, v16
	v_and_b32_e32 v107, 0xffff0000, v16
	v_lshlrev_b32_e32 v108, 16, v17
	v_and_b32_e32 v109, 0xffff0000, v17
	v_lshlrev_b32_e32 v46, 16, v30
	v_and_b32_e32 v47, 0xffff0000, v30
	v_lshlrev_b32_e32 v48, 16, v31
	v_and_b32_e32 v49, 0xffff0000, v31
	v_lshlrev_b32_e32 v30, 16, v32
	v_and_b32_e32 v31, 0xffff0000, v32
	v_lshlrev_b32_e32 v32, 16, v33
	v_and_b32_e32 v33, 0xffff0000, v33
	v_lshlrev_b32_e32 v70, 16, v6
	v_and_b32_e32 v71, 0xffff0000, v6
	v_lshlrev_b32_e32 v72, 16, v7
	v_and_b32_e32 v73, 0xffff0000, v7
	v_lshlrev_b32_e32 v78, 16, v8
	v_and_b32_e32 v79, 0xffff0000, v8
	v_lshlrev_b32_e32 v80, 16, v9
	v_and_b32_e32 v81, 0xffff0000, v9
	v_lshlrev_b32_e32 v14, 16, v26
	v_and_b32_e32 v15, 0xffff0000, v26
	v_lshlrev_b32_e32 v16, 16, v27
	v_and_b32_e32 v17, 0xffff0000, v27
	v_lshlrev_b32_e32 v6, 16, v28
	v_and_b32_e32 v7, 0xffff0000, v28
	v_lshlrev_b32_e32 v8, 16, v29
	v_and_b32_e32 v9, 0xffff0000, v29
	v_lshlrev_b32_e32 v26, 16, v34
	v_and_b32_e32 v27, 0xffff0000, v34
	v_lshlrev_b32_e32 v28, 16, v35
	v_and_b32_e32 v29, 0xffff0000, v35
	v_lshlrev_b32_e32 v34, 16, v36
	v_and_b32_e32 v35, 0xffff0000, v36
	v_lshlrev_b32_e32 v36, 16, v37
	v_and_b32_e32 v37, 0xffff0000, v37
	s_mov_b32 s53, 0
	v_lshl_add_u32 v136, v148, 1, v136
	v_mov_b32_e32 v137, v1
	v_lshl_add_u32 v138, v141, 1, v138
	v_mov_b32_e32 v139, v1
	v_readlane_b32 s20, v254, 33
	s_mov_b32 s21, s0
	s_mov_b64 s[0:1], s[22:23]
	s_barrier
	s_branch .LBB0_504

; #define PG8_STAGE(bufoff, gbase, voff) do { _Pragma("unroll") for (int _i = 0; _i < 2; ++_i) \
;     __builtin_amdgcn_global_load_lds((const unsigned*)((const char*)(gbase) + (voff)[_i]), (PG8_LAS unsigned*)(lds + (bufoff) + ldsw + _i * 8192), 16, 0, 0); } while (0)
; #define PG8_LDA(dst, b, h) do { _Pragma("unroll") for (int m = 0; m < 4; ++m) _Pragma("unroll") for (int k = 0; k < 2; ++k) dst[m][k] = *(const PG8_LAS bf16x8*)(lds + PG8_SA(b, h) + aoff + m * 2048 + k * 1024); } while (0)
; #define PG8_LDB(dst, b, h) do { _Pragma("unroll") for (int n = 0; n < 2; ++n) _Pragma("unroll") for (int k = 0; k < 2; ++k) dst[n][k] = *(const PG8_LAS bf16x8*)(lds + PG8_SB(b, h) + boff + n * 2048 + k * 1024); } while (0)
; #define PG8_MMA(ai, bj, At, Bt) do { __builtin_amdgcn_s_setprio(1); _Pragma("unroll") for (int m = 0; m < 4; ++m) _Pragma("unroll") for (int n = 0; n < 2; ++n) _Pragma("unroll") for (int k = 0; k < 2; ++k) \
;     acc[ai][bj][m][n] = __builtin_amdgcn_mfma_f32_16x16x32_bf16(Bt[n][k], At[m][k], acc[ai][bj][m][n], 0, 0, 0); __builtin_amdgcn_s_setprio(0); } while (0)
; #define PG8_WAIT_V(n) asm volatile("s_waitcnt vmcnt(" #n ")" ::: "memory")
; #define PG8_WAIT_L(n) asm volatile("s_waitcnt lgkmcnt(" #n ")" ::: "memory")
; #define PG8_BAR __builtin_amdgcn_s_barrier()
; #define PG8_SCHED __builtin_amdgcn_sched_barrier(0)
; template <class Epi>
; DI void gemm_phase(const bf16_t* __restrict__ gA, const bf16_t* __restrict__ gBt, int M, int N, int K, const Epi& E, char* lds_generic) {
;     ...
;       const bool last = (t == nt - 2);
;       const char* a1 = cA + (size_t)(t + 1) * kstep;
;       const char* a2 = last ? nA : cA + (size_t)(t + 2) * kstep; const char* b2 = last ? nB : cB + (size_t)(t + 2) * kstep;
;       const char* a3 = a2 + kstep; const char* b3 = b2 + kstep;
;       PG8_LDB(B0, 0, 0); PG8_SCHED; PG8_LDA(At, 0, 0); PG8_STAGE(PG8_SA(1, 1), a1 + hstep, voffA);
;       PG8_WAIT_L(8); PG8_BAR; PG8_WAIT_L(0); PG8_MMA(0, 0, At, B0); PG8_BAR; PG8_SCHED;
;       PG8_LDB(B1, 0, 1); PG8_STAGE(PG8_SB(0, 0), b2, voffB);
;       PG8_BAR; PG8_WAIT_L(0); PG8_MMA(0, 1, At, B1); PG8_BAR;
;       PG8_LDA(At, 0, 1); PG8_STAGE(PG8_SA(0, 0), a2, voffA);
;       PG8_BAR; PG8_WAIT_L(0); PG8_MMA(1, 0, At, B0); PG8_BAR; PG8_SCHED;
;       PG8_STAGE(PG8_SB(0, 1), b2 + hstep, voffB);
;       PG8_WAIT_V(6); PG8_BAR; PG8_MMA(1, 1, At, B1); PG8_BAR;
.LBB0_511:
	ds_read_b128 v[140:143], v146
	ds_read_b128 v[148:151], v146 offset:1024
	ds_read_b128 v[152:155], v146 offset:2048
	ds_read_b128 v[156:159], v146 offset:3072
	s_add_u32 s0, s28, 0xfffc0080
	s_addc_u32 s1, s29, -1
	s_cmp_eq_u32 s60, 12
	s_cselect_b32 s31, s22, s1
	s_cselect_b32 s30, s23, s0
	s_cselect_b32 s1, s27, s59
	s_cselect_b32 s0, s39, s58
	s_add_i32 m0, s6, 0xc000
	ds_read_b128 v[166:169], v145
	ds_read_b128 v[170:173], v145 offset:1024
	ds_read_b128 v[174:177], v145 offset:2048
	ds_read_b128 v[178:181], v145 offset:3072
	ds_read_b128 v[182:185], v145 offset:4096
	ds_read_b128 v[186:189], v145 offset:5120
	ds_read_b128 v[190:193], v145 offset:6144
	ds_read_b128 v[194:197], v145 offset:7168
	global_load_lds_dwordx4 v136, s[28:29]
	s_add_i32 m0, s6, 0xe000
	s_nop 0
	global_load_lds_dwordx4 v138, s[28:29]
	s_barrier
	s_waitcnt lgkmcnt(0)
	s_waitcnt lgkmcnt(0)
	v_mfma_f32_16x16x32_bf16 v[118:121], v[140:143], v[166:169], v[118:121]
	v_mfma_f32_16x16x32_bf16 v[110:113], v[152:155], v[166:169], v[110:113]
	v_mfma_f32_16x16x32_bf16 v[90:93], v[140:143], v[174:177], v[90:93]
	v_mfma_f32_16x16x32_bf16 v[82:85], v[152:155], v[174:177], v[82:85]
	v_mfma_f32_16x16x32_bf16 v[62:65], v[140:143], v[182:185], v[62:65]
	v_mfma_f32_16x16x32_bf16 v[50:53], v[152:155], v[182:185], v[50:53]
	v_mfma_f32_16x16x32_bf16 v[42:45], v[140:143], v[190:193], v[42:45]
	v_mfma_f32_16x16x32_bf16 v[22:25], v[152:155], v[190:193], v[22:25]
	v_mfma_f32_16x16x32_bf16 v[118:121], v[148:151], v[170:173], v[118:121]
	v_mfma_f32_16x16x32_bf16 v[110:113], v[156:159], v[170:173], v[110:113]
	v_mfma_f32_16x16x32_bf16 v[90:93], v[148:151], v[178:181], v[90:93]
	v_mfma_f32_16x16x32_bf16 v[82:85], v[156:159], v[178:181], v[82:85]
	v_mfma_f32_16x16x32_bf16 v[62:65], v[148:151], v[186:189], v[62:65]
	v_mfma_f32_16x16x32_bf16 v[50:53], v[156:159], v[186:189], v[50:53]
	v_mfma_f32_16x16x32_bf16 v[42:45], v[148:151], v[194:197], v[42:45]
	v_mfma_f32_16x16x32_bf16 v[22:25], v[156:159], v[194:197], v[22:25]
	s_barrier
	ds_read_b128 v[198:201], v146 offset:16384
	ds_read_b128 v[202:205], v146 offset:17408
	s_mov_b32 m0, s7
	ds_read_b128 v[206:209], v146 offset:18432
	ds_read_b128 v[210:213], v146 offset:19456
	global_load_lds_dwordx4 v0, s[0:1]
	s_mov_b32 m0, s12
	s_nop 0
	global_load_lds_dwordx4 v130, s[0:1]
	s_barrier
	s_waitcnt lgkmcnt(0)
	s_waitcnt lgkmcnt(0)
	v_mfma_f32_16x16x32_bf16 v[122:125], v[198:201], v[166:169], v[122:125]
	v_mfma_f32_16x16x32_bf16 v[126:129], v[206:209], v[166:169], v[126:129]
	v_mfma_f32_16x16x32_bf16 v[102:105], v[198:201], v[174:177], v[102:105]
	v_mfma_f32_16x16x32_bf16 v[114:117], v[206:209], v[174:177], v[114:117]
	v_mfma_f32_16x16x32_bf16 v[86:89], v[198:201], v[182:185], v[86:89]
	v_mfma_f32_16x16x32_bf16 v[98:101], v[206:209], v[182:185], v[98:101]
	v_mfma_f32_16x16x32_bf16 v[58:61], v[198:201], v[190:193], v[58:61]
	v_mfma_f32_16x16x32_bf16 v[74:77], v[206:209], v[190:193], v[74:77]
	v_mfma_f32_16x16x32_bf16 v[122:125], v[202:205], v[170:173], v[122:125]
	v_mfma_f32_16x16x32_bf16 v[126:129], v[210:213], v[170:173], v[126:129]
	v_mfma_f32_16x16x32_bf16 v[102:105], v[202:205], v[178:181], v[102:105]
	v_mfma_f32_16x16x32_bf16 v[114:117], v[210:213], v[178:181], v[114:117]
	v_mfma_f32_16x16x32_bf16 v[86:89], v[202:205], v[186:189], v[86:89]
	v_mfma_f32_16x16x32_bf16 v[98:101], v[210:213], v[186:189], v[98:101]
	v_mfma_f32_16x16x32_bf16 v[58:61], v[202:205], v[194:197], v[58:61]
	v_mfma_f32_16x16x32_bf16 v[74:77], v[210:213], v[194:197], v[74:77]
	s_mov_b32 m0, s6
	s_barrier
	ds_read_b128 v[166:169], v145 offset:16384
	ds_read_b128 v[170:173], v145 offset:17408
	ds_read_b128 v[174:177], v145 offset:18432
	ds_read_b128 v[178:181], v145 offset:19456
	ds_read_b128 v[182:185], v145 offset:20480
	ds_read_b128 v[186:189], v145 offset:21504
	ds_read_b128 v[190:193], v145 offset:22528
	ds_read_b128 v[194:197], v145 offset:23552
	global_load_lds_dwordx4 v134, s[30:31]
	s_mov_b32 m0, s13
	s_nop 0
	global_load_lds_dwordx4 v132, s[30:31]
	s_barrier
	s_waitcnt lgkmcnt(0)
	s_waitcnt lgkmcnt(0)
	v_mfma_f32_16x16x32_bf16 v[38:41], v[140:143], v[166:169], v[38:41]
	v_mfma_f32_16x16x32_bf16 v[18:21], v[152:155], v[166:169], v[18:21]
	v_mfma_f32_16x16x32_bf16 v[10:13], v[140:143], v[174:177], v[10:13]
	v_mfma_f32_16x16x32_bf16 v[2:5], v[152:155], v[174:177], v[2:5]
	v_mfma_f32_16x16x32_bf16 v[46:49], v[140:143], v[182:185], v[46:49]
	v_mfma_f32_16x16x32_bf16 v[30:33], v[152:155], v[182:185], v[30:33]
	v_mfma_f32_16x16x32_bf16 v[14:17], v[140:143], v[190:193], v[14:17]
	v_mfma_f32_16x16x32_bf16 v[6:9], v[152:155], v[190:193], v[6:9]
	v_mfma_f32_16x16x32_bf16 v[38:41], v[148:151], v[170:173], v[38:41]
	v_mfma_f32_16x16x32_bf16 v[18:21], v[156:159], v[170:173], v[18:21]
	v_mfma_f32_16x16x32_bf16 v[10:13], v[148:151], v[178:181], v[10:13]
	v_mfma_f32_16x16x32_bf16 v[2:5], v[156:159], v[178:181], v[2:5]
	v_mfma_f32_16x16x32_bf16 v[46:49], v[148:151], v[186:189], v[46:49]
	v_mfma_f32_16x16x32_bf16 v[30:33], v[156:159], v[186:189], v[30:33]
	v_mfma_f32_16x16x32_bf16 v[14:17], v[148:151], v[194:197], v[14:17]
	v_mfma_f32_16x16x32_bf16 v[6:9], v[156:159], v[194:197], v[6:9]
	s_barrier
	s_add_u32 s80, s0, 0x40000
	s_addc_u32 s81, s1, 0
	s_mov_b32 m0, s14
	s_nop 0
	global_load_lds_dwordx4 v0, s[80:81]
	s_mov_b32 m0, s15
	s_nop 0
	global_load_lds_dwordx4 v130, s[80:81]
	s_waitcnt vmcnt(6)
	s_barrier
; #define PG8_STAGE(bufoff, gbase, voff) do { _Pragma("unroll") for (int _i = 0; _i < 2; ++_i) \
;     __builtin_amdgcn_global_load_lds((const unsigned*)((const char*)(gbase) + (voff)[_i]), (PG8_LAS unsigned*)(lds + (bufoff) + ldsw + _i * 8192), 16, 0, 0); } while (0)
; #define PG8_LDA(dst, b, h) do { _Pragma("unroll") for (int m = 0; m < 4; ++m) _Pragma("unroll") for (int k = 0; k < 2; ++k) dst[m][k] = *(const PG8_LAS bf16x8*)(lds + PG8_SA(b, h) + aoff + m * 2048 + k * 1024); } while (0)
; #define PG8_LDB(dst, b, h) do { _Pragma("unroll") for (int n = 0; n < 2; ++n) _Pragma("unroll") for (int k = 0; k < 2; ++k) dst[n][k] = *(const PG8_LAS bf16x8*)(lds + PG8_SB(b, h) + boff + n * 2048 + k * 1024); } while (0)
; #define PG8_MMA(ai, bj, At, Bt) do { __builtin_amdgcn_s_setprio(1); _Pragma("unroll") for (int m = 0; m < 4; ++m) _Pragma("unroll") for (int n = 0; n < 2; ++n) _Pragma("unroll") for (int k = 0; k < 2; ++k) \
;     acc[ai][bj][m][n] = __builtin_amdgcn_mfma_f32_16x16x32_bf16(Bt[n][k], At[m][k], acc[ai][bj][m][n], 0, 0, 0); __builtin_amdgcn_s_setprio(0); } while (0)
; #define PG8_WAIT_V(n) asm volatile("s_waitcnt vmcnt(" #n ")" ::: "memory")
; #define PG8_WAIT_L(n) asm volatile("s_waitcnt lgkmcnt(" #n ")" ::: "memory")
; #define PG8_BAR __builtin_amdgcn_s_barrier()
; #define PG8_SCHED __builtin_amdgcn_sched_barrier(0)
; template <class Epi>
; DI void gemm_phase(const bf16_t* __restrict__ gA, const bf16_t* __restrict__ gBt, int M, int N, int K, const Epi& E, char* lds_generic) {
;     ...
;       PG8_LDB(B0, 1, 0); PG8_SCHED; PG8_LDA(At, 1, 0); PG8_STAGE(PG8_SA(0, 1), a2 + hstep, voffA);
;       PG8_WAIT_L(8); PG8_BAR; PG8_WAIT_L(0); PG8_MMA(0, 0, At, B0); PG8_BAR; PG8_SCHED;
;       PG8_LDB(B1, 1, 1); PG8_STAGE(PG8_SB(1, 0), b3, voffB);
;       PG8_BAR; PG8_WAIT_L(0); PG8_MMA(0, 1, At, B1); PG8_BAR;
;       PG8_LDA(At, 1, 1); PG8_STAGE(PG8_SA(1, 0), a3, voffA);
;       PG8_BAR; PG8_WAIT_L(0); PG8_MMA(1, 0, At, B0); PG8_BAR; PG8_SCHED;
;       PG8_STAGE(PG8_SB(1, 1), b3 + hstep, voffB);
;       PG8_WAIT_V(6); PG8_BAR; PG8_MMA(1, 1, At, B1); PG8_BAR;
	v_mfma_f32_16x16x32_bf16 v[54:57], v[198:201], v[166:169], v[54:57]
	v_mfma_f32_16x16x32_bf16 v[66:69], v[206:209], v[166:169], v[66:69]
	v_mfma_f32_16x16x32_bf16 v[94:97], v[198:201], v[174:177], v[94:97]
	v_mfma_f32_16x16x32_bf16 v[106:109], v[206:209], v[174:177], v[106:109]
	v_mfma_f32_16x16x32_bf16 v[70:73], v[198:201], v[182:185], v[70:73]
	v_mfma_f32_16x16x32_bf16 v[78:81], v[206:209], v[182:185], v[78:81]
	v_mfma_f32_16x16x32_bf16 v[26:29], v[198:201], v[190:193], v[26:29]
	v_mfma_f32_16x16x32_bf16 v[34:37], v[206:209], v[190:193], v[34:37]
	v_mfma_f32_16x16x32_bf16 v[54:57], v[202:205], v[170:173], v[54:57]
	v_mfma_f32_16x16x32_bf16 v[66:69], v[210:213], v[170:173], v[66:69]
	v_mfma_f32_16x16x32_bf16 v[94:97], v[202:205], v[178:181], v[94:97]
	v_mfma_f32_16x16x32_bf16 v[106:109], v[210:213], v[178:181], v[106:109]
	v_mfma_f32_16x16x32_bf16 v[70:73], v[202:205], v[186:189], v[70:73]
	v_mfma_f32_16x16x32_bf16 v[78:81], v[210:213], v[186:189], v[78:81]
	v_mfma_f32_16x16x32_bf16 v[26:29], v[202:205], v[194:197], v[26:29]
	v_mfma_f32_16x16x32_bf16 v[34:37], v[210:213], v[194:197], v[34:37]
	s_barrier
	ds_read_b128 v[140:143], v146 offset:32768
	ds_read_b128 v[148:151], v146 offset:33792
	ds_read_b128 v[152:155], v146 offset:34816
	ds_read_b128 v[156:159], v146 offset:35840
	s_add_u32 s30, s30, 0x40000
	s_addc_u32 s31, s31, 0
	s_mov_b32 m0, s16
	ds_read_b128 v[166:169], v145 offset:32768
	ds_read_b128 v[170:173], v145 offset:33792
	ds_read_b128 v[174:177], v145 offset:34816
	ds_read_b128 v[178:181], v145 offset:35840
	ds_read_b128 v[182:185], v145 offset:36864
	ds_read_b128 v[186:189], v145 offset:37888
	ds_read_b128 v[190:193], v145 offset:38912
	ds_read_b128 v[194:197], v145 offset:39936
	global_load_lds_dwordx4 v134, s[30:31]
	s_mov_b32 m0, s18
	s_nop 0
	global_load_lds_dwordx4 v132, s[30:31]
	s_barrier
	s_waitcnt lgkmcnt(0)
	s_waitcnt lgkmcnt(0)
	v_mfma_f32_16x16x32_bf16 v[118:121], v[140:143], v[166:169], v[118:121]
	v_mfma_f32_16x16x32_bf16 v[110:113], v[152:155], v[166:169], v[110:113]
	v_mfma_f32_16x16x32_bf16 v[90:93], v[140:143], v[174:177], v[90:93]
	v_mfma_f32_16x16x32_bf16 v[82:85], v[152:155], v[174:177], v[82:85]
	v_mfma_f32_16x16x32_bf16 v[62:65], v[140:143], v[182:185], v[62:65]
	v_mfma_f32_16x16x32_bf16 v[50:53], v[152:155], v[182:185], v[50:53]
	v_mfma_f32_16x16x32_bf16 v[42:45], v[140:143], v[190:193], v[42:45]
	v_mfma_f32_16x16x32_bf16 v[22:25], v[152:155], v[190:193], v[22:25]
	v_mfma_f32_16x16x32_bf16 v[118:121], v[148:151], v[170:173], v[118:121]
	v_mfma_f32_16x16x32_bf16 v[110:113], v[156:159], v[170:173], v[110:113]
	v_mfma_f32_16x16x32_bf16 v[90:93], v[148:151], v[178:181], v[90:93]
	v_mfma_f32_16x16x32_bf16 v[82:85], v[156:159], v[178:181], v[82:85]
	v_mfma_f32_16x16x32_bf16 v[62:65], v[148:151], v[186:189], v[62:65]
	v_mfma_f32_16x16x32_bf16 v[50:53], v[156:159], v[186:189], v[50:53]
	v_mfma_f32_16x16x32_bf16 v[42:45], v[148:151], v[194:197], v[42:45]
	v_mfma_f32_16x16x32_bf16 v[22:25], v[156:159], v[194:197], v[22:25]
	s_barrier
	s_mov_b32 m0, s8
	ds_read_b128 v[198:201], v146 offset:49152
	ds_read_b128 v[202:205], v146 offset:50176
	ds_read_b128 v[206:209], v146 offset:51200
	ds_read_b128 v[210:213], v146 offset:52224
	s_add_u32 s80, s0, 0x80
	s_addc_u32 s81, s1, 0
	global_load_lds_dwordx4 v0, s[80:81]
	s_mov_b32 m0, s9
	s_nop 0
	s_add_u32 s80, s0, 0x80
	s_addc_u32 s81, s1, 0
	global_load_lds_dwordx4 v130, s[80:81]
	s_barrier
	s_waitcnt lgkmcnt(0)
	s_waitcnt lgkmcnt(0)
	v_mfma_f32_16x16x32_bf16 v[122:125], v[198:201], v[166:169], v[122:125]
	v_mfma_f32_16x16x32_bf16 v[126:129], v[206:209], v[166:169], v[126:129]
	v_mfma_f32_16x16x32_bf16 v[102:105], v[198:201], v[174:177], v[102:105]
	v_mfma_f32_16x16x32_bf16 v[114:117], v[206:209], v[174:177], v[114:117]
	v_mfma_f32_16x16x32_bf16 v[86:89], v[198:201], v[182:185], v[86:89]
	v_mfma_f32_16x16x32_bf16 v[98:101], v[206:209], v[182:185], v[98:101]
	v_mfma_f32_16x16x32_bf16 v[58:61], v[198:201], v[190:193], v[58:61]
	v_mfma_f32_16x16x32_bf16 v[74:77], v[206:209], v[190:193], v[74:77]
	v_mfma_f32_16x16x32_bf16 v[122:125], v[202:205], v[170:173], v[122:125]
	v_mfma_f32_16x16x32_bf16 v[126:129], v[210:213], v[170:173], v[126:129]
	v_mfma_f32_16x16x32_bf16 v[102:105], v[202:205], v[178:181], v[102:105]
	v_mfma_f32_16x16x32_bf16 v[114:117], v[210:213], v[178:181], v[114:117]
	v_mfma_f32_16x16x32_bf16 v[86:89], v[202:205], v[186:189], v[86:89]
	v_mfma_f32_16x16x32_bf16 v[98:101], v[210:213], v[186:189], v[98:101]
	v_mfma_f32_16x16x32_bf16 v[58:61], v[202:205], v[194:197], v[58:61]
	v_mfma_f32_16x16x32_bf16 v[74:77], v[210:213], v[194:197], v[74:77]
	s_mov_b32 m0, s19
	s_barrier
	ds_read_b128 v[166:169], v145 offset:49152
	ds_read_b128 v[170:173], v145 offset:50176
	ds_read_b128 v[174:177], v145 offset:51200
	ds_read_b128 v[178:181], v145 offset:52224
	ds_read_b128 v[182:185], v145 offset:53248
	ds_read_b128 v[186:189], v145 offset:54272
	ds_read_b128 v[190:193], v145 offset:55296
	ds_read_b128 v[194:197], v145 offset:56320
	s_add_u32 s80, s30, 0xfffc0080
	s_addc_u32 s81, s31, -1
	global_load_lds_dwordx4 v134, s[80:81]
	s_mov_b32 m0, s33
	s_nop 0
	s_add_u32 s80, s30, 0xfffc0080
	s_addc_u32 s81, s31, -1
	global_load_lds_dwordx4 v132, s[80:81]
	s_barrier
; DI bf16_t f2bf(float x) { unsigned u = __float_as_uint(x); u += 0x7fffu + ((u >> 16) & 1u); return (bf16_t)(u >> 16); }
; DI unsigned pack2(float lo, float hi) { f32x2_t v = {lo, hi}; return __builtin_bit_cast(unsigned, __builtin_convertvector(v, bf16x2_t)); }
; #define PG8_STAGE(bufoff, gbase, voff) do { _Pragma("unroll") for (int _i = 0; _i < 2; ++_i) \
;     __builtin_amdgcn_global_load_lds((const unsigned*)((const char*)(gbase) + (voff)[_i]), (PG8_LAS unsigned*)(lds + (bufoff) + ldsw + _i * 8192), 16, 0, 0); } while (0)
; #define PG8_MMA(ai, bj, At, Bt) do { __builtin_amdgcn_s_setprio(1); _Pragma("unroll") for (int m = 0; m < 4; ++m) _Pragma("unroll") for (int n = 0; n < 2; ++n) _Pragma("unroll") for (int k = 0; k < 2; ++k) \
;     acc[ai][bj][m][n] = __builtin_amdgcn_mfma_f32_16x16x32_bf16(Bt[n][k], At[m][k], acc[ai][bj][m][n], 0, 0, 0); __builtin_amdgcn_s_setprio(0); } while (0)
; #define PG8_WAIT_V(n) asm volatile("s_waitcnt vmcnt(" #n ")" ::: "memory")
; #define PG8_WAIT_L(n) asm volatile("s_waitcnt lgkmcnt(" #n ")" ::: "memory")
; #define PG8_BAR __builtin_amdgcn_s_barrier()
; #define PG8_SCHED __builtin_amdgcn_sched_barrier(0)
;   DI void operator()(const f32x4 (&acc)[2][2][4][2], const Unit& u, int wr, int wc, int fr, int fq, const PG8_LAS float*) const {
;     ...
;       for (int m = 0; m < 4; ++m) { const int row = row0 + ai * HALF + m * 16; bf16_t* rowp = dst + (size_t)row * DM + col0; float ss = 0.f;
; #pragma unroll
;         for (int bj = 0; bj < 2; ++bj) { const f32x4 v0 = acc[ai][bj][m][0] * coef, v1 = acc[ai][bj][m][1] * coef;
;           ss += v0[0] * v0[0] + v0[1] * v0[1] + v0[2] * v0[2] + v0[3] * v0[3] + v1[0] * v1[0] + v1[1] * v1[1] + v1[2] * v1[2] + v1[3] * v1[3];
;           u32x4 w; w.x = pack2(v0[0], v0[1]); w.y = pack2(v0[2], v0[3]); w.z = pack2(v1[0], v1[1]); w.w = pack2(v1[2], v1[3]);
;           *(u32x4*)(rowp + bj * HALF) = w; }
;         ss += __shfl_xor(ss, 16); ss += __shfl_xor(ss, 32);
;         if (fq == 0) ssq[(size_t)row * 16 + u.pn * 4 + wc] = f2bf(ss); }
; template <class Epi>
; DI void gemm_phase(const bf16_t* __restrict__ gA, const bf16_t* __restrict__ gBt, int M, int N, int K, const Epi& E, char* lds_generic) {
;     ...
;       PG8_BAR; PG8_WAIT_L(0); PG8_MMA(1, 0, At, B0); PG8_BAR; PG8_SCHED;
;       PG8_STAGE(PG8_SB(1, 1), b3 + hstep, voffB);
;       PG8_WAIT_V(6); PG8_BAR; PG8_MMA(1, 1, At, B1); PG8_BAR;
	s_waitcnt lgkmcnt(0)
	s_waitcnt lgkmcnt(0)
	v_mfma_f32_16x16x32_bf16 v[38:41], v[140:143], v[166:169], v[38:41]
	v_mfma_f32_16x16x32_bf16 v[18:21], v[152:155], v[166:169], v[18:21]
	v_mfma_f32_16x16x32_bf16 v[10:13], v[140:143], v[174:177], v[10:13]
	v_mfma_f32_16x16x32_bf16 v[2:5], v[152:155], v[174:177], v[2:5]
	v_mfma_f32_16x16x32_bf16 v[46:49], v[140:143], v[182:185], v[46:49]
	v_mfma_f32_16x16x32_bf16 v[30:33], v[152:155], v[182:185], v[30:33]
	v_mfma_f32_16x16x32_bf16 v[14:17], v[140:143], v[190:193], v[14:17]
	v_mfma_f32_16x16x32_bf16 v[6:9], v[152:155], v[190:193], v[6:9]
	v_mfma_f32_16x16x32_bf16 v[38:41], v[148:151], v[170:173], v[38:41]
	v_mfma_f32_16x16x32_bf16 v[18:21], v[156:159], v[170:173], v[18:21]
	v_mfma_f32_16x16x32_bf16 v[10:13], v[148:151], v[178:181], v[10:13]
	v_mfma_f32_16x16x32_bf16 v[2:5], v[156:159], v[178:181], v[2:5]
	v_mfma_f32_16x16x32_bf16 v[46:49], v[148:151], v[186:189], v[46:49]
	v_mfma_f32_16x16x32_bf16 v[30:33], v[156:159], v[186:189], v[30:33]
	v_mfma_f32_16x16x32_bf16 v[14:17], v[148:151], v[194:197], v[14:17]
	v_mfma_f32_16x16x32_bf16 v[6:9], v[156:159], v[194:197], v[6:9]
	s_barrier
	s_add_u32 s0, s0, 0x40080
	s_addc_u32 s1, s1, 0
	s_mov_b32 m0, s35
	s_nop 0
	global_load_lds_dwordx4 v0, s[0:1]
	s_mov_b32 m0, s42
	s_nop 0
	global_load_lds_dwordx4 v130, s[0:1]
	s_waitcnt vmcnt(6)
	s_barrier
	v_mfma_f32_16x16x32_bf16 v[54:57], v[198:201], v[166:169], v[54:57]
	v_mfma_f32_16x16x32_bf16 v[66:69], v[206:209], v[166:169], v[66:69]
	v_mfma_f32_16x16x32_bf16 v[94:97], v[198:201], v[174:177], v[94:97]
	v_mfma_f32_16x16x32_bf16 v[106:109], v[206:209], v[174:177], v[106:109]
	v_mfma_f32_16x16x32_bf16 v[70:73], v[198:201], v[182:185], v[70:73]
	v_mfma_f32_16x16x32_bf16 v[78:81], v[206:209], v[182:185], v[78:81]
	v_mfma_f32_16x16x32_bf16 v[26:29], v[198:201], v[190:193], v[26:29]
	v_mfma_f32_16x16x32_bf16 v[34:37], v[206:209], v[190:193], v[34:37]
	v_mfma_f32_16x16x32_bf16 v[54:57], v[202:205], v[170:173], v[54:57]
	v_mfma_f32_16x16x32_bf16 v[66:69], v[210:213], v[170:173], v[66:69]
	v_mfma_f32_16x16x32_bf16 v[94:97], v[202:205], v[178:181], v[94:97]
	v_mfma_f32_16x16x32_bf16 v[106:109], v[210:213], v[178:181], v[106:109]
	v_mfma_f32_16x16x32_bf16 v[70:73], v[202:205], v[186:189], v[70:73]
	v_mfma_f32_16x16x32_bf16 v[78:81], v[210:213], v[186:189], v[78:81]
	v_mfma_f32_16x16x32_bf16 v[26:29], v[202:205], v[194:197], v[26:29]
	v_mfma_f32_16x16x32_bf16 v[34:37], v[210:213], v[194:197], v[34:37]
	s_add_i32 s60, s60, 2
	s_add_u32 s28, s28, 0x100
	s_addc_u32 s29, s29, 0
	s_add_u32 s58, s58, 0x100
	s_addc_u32 s59, s59, 0
	s_cmp_gt_u32 s60, 13
	s_barrier
	s_cbranch_scc0 .LBB0_511
	v_mul_f32_e32 v152, v119, v119
	v_fmac_f32_e32 v152, v118, v118
	v_fmac_f32_e32 v152, v120, v120
	v_cvt_pk_bf16_f32 v118, v118, v119
	v_cvt_pk_bf16_f32 v119, v120, v121
	v_mul_f32_e32 v120, v123, v123
	v_fmac_f32_e32 v120, v122, v122
	v_fmac_f32_e32 v120, v124, v124
	v_fmac_f32_e32 v152, v121, v121
	v_fmac_f32_e32 v120, v125, v125
	v_fmac_f32_e32 v152, v110, v110
	v_fmac_f32_e32 v120, v126, v126
	v_xor_b32_e32 v143, 16, v223
	v_fmac_f32_e32 v152, v111, v111
	v_fmac_f32_e32 v120, v127, v127
	v_cmp_lt_i32_e64 s[0:1], v143, v225
	v_fmac_f32_e32 v152, v112, v112
	v_fmac_f32_e32 v120, v128, v128
	v_cndmask_b32_e64 v143, v223, v143, s[0:1]
	v_fmac_f32_e32 v152, v113, v113
	v_fmac_f32_e32 v120, v129, v129
	v_lshlrev_b32_e32 v149, 2, v143
	v_add_f32_e32 v152, v152, v120
	ds_bpermute_b32 v153, v149, v152
	v_xor_b32_e32 v143, 32, v223
	v_cmp_lt_i32_e64 s[0:1], v143, v225
	v_lshl_add_u32 v142, s21, 8, v144
	v_cvt_pk_bf16_f32 v120, v110, v111
	v_cndmask_b32_e64 v143, v223, v143, s[0:1]
	v_lshlrev_b32_e32 v148, 2, v143
	s_waitcnt lgkmcnt(0)
	v_add_f32_e32 v110, v152, v153
	v_ashrrev_i32_e32 v143, 31, v142
	ds_bpermute_b32 v111, v148, v110
	v_lshl_or_b32 v140, s20, 8, v147
	v_lshlrev_b64 v[150:151], 11, v[142:143]
	v_ashrrev_i32_e32 v141, 31, v140
	v_lshl_add_u64 v[150:151], s[92:93], 0, v[150:151]
	s_lshl_b32 s0, s20, 2
	v_lshl_add_u64 v[150:151], v[140:141], 1, v[150:151]
	v_cvt_pk_bf16_f32 v121, v112, v113
	s_ashr_i32 s1, s0, 31
	global_store_dwordx4 v[150:151], v[118:121], off
	s_nop 1
	v_cvt_pk_bf16_f32 v118, v122, v123
	v_cvt_pk_bf16_f32 v119, v124, v125
	v_cvt_pk_bf16_f32 v120, v126, v127
	v_cvt_pk_bf16_f32 v121, v128, v129
	global_store_dwordx4 v[150:151], v[118:121], off offset:256
	s_and_saveexec_b64 s[28:29], s[36:37]
	s_cbranch_execz .LBB0_514
	s_waitcnt lgkmcnt(0)
	v_add_f32_e32 v110, v110, v111
	v_bfe_u32 v111, v110, 16, 1
	v_add3_u32 v112, v110, v111, s63
	v_lshlrev_b64 v[110:111], 5, v[142:143]
	v_lshl_add_u64 v[110:111], s[70:71], 0, v[110:111]
	v_lshl_add_u64 v[110:111], s[0:1], 1, v[110:111]
	s_lshl_b32 s76, s5, 1
	v_lshl_add_u64 v[110:111], v[110:111], 0, s[76:77]
	global_store_short_d16_hi v[110:111], v112, off

;   DI void init(f32x4 (&acc)[2][2][4][2], const Unit&, int, int, int, int) const { acc_zero(acc); }
;   DI void init(f32x4 (&acc)[2][2][4][2], const Unit&, int, int, int, int) const { acc_zero(acc); }
; #define PG8_STAGE(bufoff, gbase, voff) do { _Pragma("unroll") for (int _i = 0; _i < 2; ++_i) \
;     __builtin_amdgcn_global_load_lds((const unsigned*)((const char*)(gbase) + (voff)[_i]), (PG8_LAS unsigned*)(lds + (bufoff) + ldsw + _i * 8192), 16, 0, 0); } while (0)
; #define PG8_WAIT_V(n) asm volatile("s_waitcnt vmcnt(" #n ")" ::: "memory")
; #define PG8_BAR __builtin_amdgcn_s_barrier()
; #define PG8_RTAB_LOAD(var, unit) do { if constexpr (Epi::NEEDS_R) { var = *(const uint4*)(E.ssq + (size_t)((unit).pm * BM + (tid >> 1)) * 16 + (tid & 1) * 8); } } while (0)
; template <class Epi>
; DI void gemm_phase(const bf16_t* __restrict__ gA, const bf16_t* __restrict__ gBt, int M, int N, int K, const Epi& E, char* lds_generic) {
;     ...
;   for (int i = 0; i < 2; ++i) { int R, C; stage_rc(tid * 16 + i * 8192, R, C); const int Rb = Epi::PERM ? ((R & ~31) + perm32(R & 31)) : R;
;     voffA[i] = (unsigned)(R * K + C) * 2u; voffB[i] = (unsigned)(Rb * K + C) * 2u; }
;   const size_t kstep = (size_t)(BK * 2);
;   const size_t hstep = (size_t)HALF * K * 2;
;   const size_t tstep = 2 * hstep;
;   const unsigned ldsw = (unsigned)wid * 1024u;
;   const int aoff = lds_byte(wr * 64 + fr, fq * 8), boff = lds_byte(wc * 32 + fr, fq * 8);
;     ...
;   Unit cur, nxt; int ui = 0;
;   if (!S.next(0, cur)) return;
;   f32x4 acc[2][2][4][2];
;   E.init(acc, cur, wr, wc, fr, fq);
;     ...
;   { uint4 rt0_ = {0u, 0u, 0u, 0u}; PG8_RTAB_LOAD(rt0_, cur); PG8_RTAB_FIN(rt0_, 0); }
;   bf16x8 At[4][2], B0[2][2], B1[2][2];
;   const char* cA = (const char*)gA + (size_t)cur.pm * tstep; const char* cB = (const char*)gBt + (size_t)cur.pn * tstep;
;   PG8_STAGE(PG8_SB(0, 0), cB, voffB); PG8_STAGE(PG8_SA(0, 0), cA, voffA); PG8_STAGE(PG8_SB(0, 1), cB + hstep, voffB); PG8_STAGE(PG8_SA(0, 1), cA + hstep, voffA);
;   if (wr == 1) PG8_BAR;
;   PG8_WAIT_V(4); PG8_BAR;
;   PG8_STAGE(PG8_SB(1, 0), cB + kstep, voffB); PG8_STAGE(PG8_SA(1, 0), cA + kstep, voffA); PG8_STAGE(PG8_SB(1, 1), cB + hstep + kstep, voffB);
;   PG8_WAIT_V(6); PG8_BAR;
.LBB0_595:
	v_and_b32_e32 v18, 15, v2
	v_lshrrev_b32_e32 v2, 1, v2
	v_and_b32_e32 v2, 24, v2
	v_lshl_add_u64 v[10:11], s[40:41], 0, v[0:1]
	v_mov_b32_e32 v139, v1
	v_lshlrev_b32_e32 v19, 1, v2
	s_add_i32 s13, s72, 0x18000
	v_lshl_add_u64 v[12:13], s[40:41], 0, v[138:139]
	v_mov_b32_e32 v135, v1
	v_lshl_or_b32 v153, s8, 6, v18
	v_lshl_or_b32 v19, v18, 6, v19
	v_lshlrev_b32_e32 v18, 2, v18
	v_lshl_add_u64 v[10:11], v[10:11], 0, s[10:11]
	s_mov_b32 m0, s13
	s_add_i32 s35, s72, 0x1a000
	v_lshl_add_u64 v[14:15], s[28:29], 0, v[134:135]
	v_mov_b32_e32 v137, v1
	s_lshl_b32 s9, s8, 13
	v_and_b32_e32 v20, 32, v18
	s_lshl_b32 s6, s6, 5
	global_load_lds_dwordx4 v[10:11], off
	v_lshl_add_u64 v[10:11], v[12:13], 0, s[10:11]
	s_mov_b32 m0, s35
	s_add_i32 s53, s72, 0x8000
	v_lshl_add_u64 v[16:17], s[28:29], 0, v[136:137]
	v_bitop3_b32 v154, v19, s9, v20 bitop3:0xde
	s_and_b32 s9, s6, 0x60
	global_load_lds_dwordx4 v[10:11], off
	v_lshl_add_u64 v[10:11], v[14:15], 0, s[10:11]
	s_mov_b32 m0, s53
	s_add_i32 s74, s72, 0xa000
	s_lshl_b32 s6, s9, 7
	global_load_lds_dwordx4 v[10:11], off
	v_lshl_add_u64 v[10:11], v[16:17], 0, s[10:11]
	s_mov_b32 m0, s74
	s_add_i32 s60, s72, 0x1c000
	v_bitop3_b32 v155, v19, s6, v20 bitop3:0xde
	v_add_u32_e32 v155, 0x10000, v155
	global_load_lds_dwordx4 v[10:11], off
	v_lshl_add_u64 v[10:11], s[80:81], 0, v[0:1]
	s_mov_b32 m0, s60
	s_add_i32 s6, s72, 0x1e000
	global_load_lds_dwordx4 v[10:11], off
	v_lshl_add_u64 v[10:11], s[80:81], 0, v[138:139]
	s_mov_b32 m0, s6
	v_or_b32_e32 v157, s9, v2
	global_load_lds_dwordx4 v[10:11], off
	s_waitcnt vmcnt(10)
	s_barrier
	v_lshlrev_b32_e32 v2, 14, v3
	v_and_b32_e32 v2, 0xffff8000, v2
	v_lshl_add_u32 v2, v5, 11, v2
	v_and_b32_e32 v3, 1, v3
	v_lshl_or_b32 v2, v3, 6, v2
	v_lshl_add_u32 v142, v6, 1, v2
	v_lshlrev_b32_e32 v2, 14, v7
	v_and_b32_e32 v2, 0xffff8000, v2
	v_lshlrev_b32_e32 v4, 3, v4
	s_waitcnt vmcnt(6)
	s_lshl_b32 s8, s8, 8
	v_lshl_add_u32 v2, v8, 11, v2
	v_and_b32_e32 v3, 1, v7
	v_readlane_b32 s18, v255, 27
	v_lshlrev_b32_e32 v10, 1, v4
	v_mov_b32_e32 v11, v1
	s_add_i32 s8, s8, 0x20040
	v_lshl_or_b32 v2, v3, 6, v2
	v_readlane_b32 s19, v255, 28
	v_lshl_add_u64 v[140:141], s[84:85], 0, v[10:11]
	v_or_b32_e32 v156, s8, v18
	v_mov_b32_e32 v143, v1
	v_lshl_add_u32 v144, v9, 1, v2
	v_mov_b32_e32 v145, v1
	s_mov_b32 s8, 0
	v_readlane_b32 s9, v255, 33
	s_mov_b32 s19, s18
	s_mov_b64 s[30:31], s[40:41]
	s_barrier
	s_branch .LBB0_598

; #define PG8_STAGE(bufoff, gbase, voff) do { _Pragma("unroll") for (int _i = 0; _i < 2; ++_i) \
;     __builtin_amdgcn_global_load_lds((const unsigned*)((const char*)(gbase) + (voff)[_i]), (PG8_LAS unsigned*)(lds + (bufoff) + ldsw + _i * 8192), 16, 0, 0); } while (0)
; #define PG8_LDA(dst, b, h) do { _Pragma("unroll") for (int m = 0; m < 4; ++m) _Pragma("unroll") for (int k = 0; k < 2; ++k) dst[m][k] = *(const PG8_LAS bf16x8*)(lds + PG8_SA(b, h) + aoff + m * 2048 + k * 1024); } while (0)
; #define PG8_LDB(dst, b, h) do { _Pragma("unroll") for (int n = 0; n < 2; ++n) _Pragma("unroll") for (int k = 0; k < 2; ++k) dst[n][k] = *(const PG8_LAS bf16x8*)(lds + PG8_SB(b, h) + boff + n * 2048 + k * 1024); } while (0)
; #define PG8_MMA(ai, bj, At, Bt) do { __builtin_amdgcn_s_setprio(1); _Pragma("unroll") for (int m = 0; m < 4; ++m) _Pragma("unroll") for (int n = 0; n < 2; ++n) _Pragma("unroll") for (int k = 0; k < 2; ++k) \
;     acc[ai][bj][m][n] = __builtin_amdgcn_mfma_f32_16x16x32_bf16(Bt[n][k], At[m][k], acc[ai][bj][m][n], 0, 0, 0); __builtin_amdgcn_s_setprio(0); } while (0)
; template <class Epi>
; DI void gemm_phase(const bf16_t* __restrict__ gA, const bf16_t* __restrict__ gBt, int M, int N, int K, const Epi& E, char* lds_generic) {
;     ...
;     const bool has_next = S.next(ui + 1, nxt);
;     const char* nA = has_next ? (const char*)gA + (size_t)nxt.pm * tstep : cA; const char* nB = has_next ? (const char*)gBt + (size_t)nxt.pn * tstep : cB;
;     for (int t = 0; t < nt; t += 2) {
;       const bool last = (t == nt - 2);
;       const char* a1 = cA + (size_t)(t + 1) * kstep;
;       const char* a2 = last ? nA : cA + (size_t)(t + 2) * kstep; const char* b2 = last ? nB : cB + (size_t)(t + 2) * kstep;
;       const char* a3 = a2 + kstep; const char* b3 = b2 + kstep;
;       PG8_LDB(B0, 0, 0); PG8_SCHED; PG8_LDA(At, 0, 0); PG8_STAGE(PG8_SA(1, 1), a1 + hstep, voffA);
;       PG8_WAIT_L(8); PG8_BAR; PG8_WAIT_L(0); PG8_MMA(0, 0, At, B0); PG8_BAR; PG8_SCHED;
;       PG8_LDB(B1, 0, 1); PG8_STAGE(PG8_SB(0, 0), b2, voffB);
;       PG8_BAR; PG8_WAIT_L(0); PG8_MMA(0, 1, At, B1); PG8_BAR;
;       PG8_LDA(At, 0, 1); PG8_STAGE(PG8_SA(0, 0), a2, voffA);
;       PG8_BAR; PG8_WAIT_L(0); PG8_MMA(1, 0, At, B0); PG8_BAR; PG8_SCHED;
;       PG8_STAGE(PG8_SB(0, 1), b2 + hstep, voffB);
;       PG8_WAIT_V(6); PG8_BAR; PG8_MMA(1, 1, At, B1); PG8_BAR;
.LBB0_604:
	s_ashr_i32 s87, s86, 31
	s_lshl_b64 s[20:21], s[86:87], 19
	s_add_u32 s88, s82, s20
	s_addc_u32 s89, s83, s21
	s_and_b64 s[20:21], s[38:39], exec
	s_cselect_b32 s20, s89, s29
	s_cselect_b32 s21, s88, s28
	s_ashr_i32 s27, s26, 31
	s_lshl_b64 s[22:23], s[26:27], 19
	s_add_u32 s90, s16, s22
	s_addc_u32 s91, s4, s23
	s_and_b64 s[22:23], s[38:39], exec
	s_cselect_b32 s27, s91, s31
	s_cselect_b32 s42, s90, s30
	s_add_u32 vcc_lo, s28, 0x40080
	s_addc_u32 vcc_hi, s29, 0
	s_add_u32 s87, s30, 0x100
	s_addc_u32 s22, s31, 0
	s_mov_b32 s23, -2
	ds_read_b128 v[50:53], v155
	ds_read_b128 v[146:149], v155 offset:1024
	ds_read_b128 v[158:161], v155 offset:2048
	ds_read_b128 v[166:169], v155 offset:3072
	s_add_u32 s24, vcc_lo, 0xfffc0080
	s_addc_u32 s25, vcc_hi, -1
	s_cmp_eq_u32 s23, 12
	s_cselect_b32 s31, s20, s25
	s_cselect_b32 s30, s21, s24
	s_cselect_b32 s29, s27, s22
	s_cselect_b32 s28, s42, s87
	s_add_i32 m0, s72, 0xc000
	ds_read_b128 v[170:173], v154
	ds_read_b128 v[174:177], v154 offset:1024
	ds_read_b128 v[178:181], v154 offset:2048
	ds_read_b128 v[182:185], v154 offset:3072
	ds_read_b128 v[186:189], v154 offset:4096
	ds_read_b128 v[190:193], v154 offset:5120
	ds_read_b128 v[194:197], v154 offset:6144
	ds_read_b128 v[198:201], v154 offset:7168
	global_load_lds_dwordx4 v142, vcc
	s_add_i32 m0, s72, 0xe000
	s_nop 0
	global_load_lds_dwordx4 v144, vcc
	s_barrier
	s_waitcnt lgkmcnt(0)
	s_waitcnt lgkmcnt(0)
	v_mfma_f32_16x16x32_bf16 v[130:133], v[50:53], v[170:173], 0
	v_mfma_f32_16x16x32_bf16 v[122:125], v[158:161], v[170:173], 0
	v_mfma_f32_16x16x32_bf16 v[114:117], v[50:53], v[178:181], 0
	v_mfma_f32_16x16x32_bf16 v[106:109], v[158:161], v[178:181], 0
	v_mfma_f32_16x16x32_bf16 v[98:101], v[50:53], v[186:189], 0
	v_mfma_f32_16x16x32_bf16 v[90:93], v[158:161], v[186:189], 0
	v_mfma_f32_16x16x32_bf16 v[82:85], v[50:53], v[194:197], 0
	v_mfma_f32_16x16x32_bf16 v[74:77], v[158:161], v[194:197], 0
	v_mfma_f32_16x16x32_bf16 v[130:133], v[146:149], v[174:177], v[130:133]
	v_mfma_f32_16x16x32_bf16 v[122:125], v[166:169], v[174:177], v[122:125]
	v_mfma_f32_16x16x32_bf16 v[114:117], v[146:149], v[182:185], v[114:117]
	v_mfma_f32_16x16x32_bf16 v[106:109], v[166:169], v[182:185], v[106:109]
	v_mfma_f32_16x16x32_bf16 v[98:101], v[146:149], v[190:193], v[98:101]
	v_mfma_f32_16x16x32_bf16 v[90:93], v[166:169], v[190:193], v[90:93]
	v_mfma_f32_16x16x32_bf16 v[82:85], v[146:149], v[198:201], v[82:85]
	v_mfma_f32_16x16x32_bf16 v[74:77], v[166:169], v[198:201], v[74:77]
	s_barrier
	s_mov_b32 m0, s14
	ds_read_b128 v[202:205], v155 offset:16384
	ds_read_b128 v[206:209], v155 offset:17408
	ds_read_b128 v[210:213], v155 offset:18432
	ds_read_b128 v[214:217], v155 offset:19456
	global_load_lds_dwordx4 v0, s[28:29]
	s_mov_b32 m0, s15
	s_nop 0
	global_load_lds_dwordx4 v138, s[28:29]
	s_barrier
	s_waitcnt lgkmcnt(0)
	s_waitcnt lgkmcnt(0)
	v_mfma_f32_16x16x32_bf16 v[126:129], v[202:205], v[170:173], 0
	v_mfma_f32_16x16x32_bf16 v[118:121], v[210:213], v[170:173], 0
	v_mfma_f32_16x16x32_bf16 v[110:113], v[202:205], v[178:181], 0
	v_mfma_f32_16x16x32_bf16 v[102:105], v[210:213], v[178:181], 0
	v_mfma_f32_16x16x32_bf16 v[94:97], v[202:205], v[186:189], 0
	v_mfma_f32_16x16x32_bf16 v[86:89], v[210:213], v[186:189], 0
	v_mfma_f32_16x16x32_bf16 v[78:81], v[202:205], v[194:197], 0
	v_mfma_f32_16x16x32_bf16 v[70:73], v[210:213], v[194:197], 0
	v_mfma_f32_16x16x32_bf16 v[126:129], v[206:209], v[174:177], v[126:129]
	v_mfma_f32_16x16x32_bf16 v[118:121], v[214:217], v[174:177], v[118:121]
	v_mfma_f32_16x16x32_bf16 v[110:113], v[206:209], v[182:185], v[110:113]
	v_mfma_f32_16x16x32_bf16 v[102:105], v[214:217], v[182:185], v[102:105]
	v_mfma_f32_16x16x32_bf16 v[94:97], v[206:209], v[190:193], v[94:97]
	v_mfma_f32_16x16x32_bf16 v[86:89], v[214:217], v[190:193], v[86:89]
	v_mfma_f32_16x16x32_bf16 v[78:81], v[206:209], v[198:201], v[78:81]
	v_mfma_f32_16x16x32_bf16 v[70:73], v[214:217], v[198:201], v[70:73]
	s_mov_b32 m0, s72
	s_barrier
	ds_read_b128 v[170:173], v154 offset:16384
	ds_read_b128 v[174:177], v154 offset:17408
	ds_read_b128 v[178:181], v154 offset:18432
	ds_read_b128 v[182:185], v154 offset:19456
	ds_read_b128 v[186:189], v154 offset:20480
	ds_read_b128 v[190:193], v154 offset:21504
	ds_read_b128 v[194:197], v154 offset:22528
	ds_read_b128 v[198:201], v154 offset:23552
	global_load_lds_dwordx4 v134, s[30:31]
	s_mov_b32 m0, s58
	s_nop 0
	global_load_lds_dwordx4 v136, s[30:31]
	s_barrier
	s_waitcnt lgkmcnt(0)
	s_waitcnt lgkmcnt(0)
	v_mfma_f32_16x16x32_bf16 v[66:69], v[50:53], v[170:173], 0
	v_mfma_f32_16x16x32_bf16 v[58:61], v[158:161], v[170:173], 0
	v_mfma_f32_16x16x32_bf16 v[46:49], v[50:53], v[178:181], 0
	v_mfma_f32_16x16x32_bf16 v[38:41], v[158:161], v[178:181], 0
	v_mfma_f32_16x16x32_bf16 v[30:33], v[50:53], v[186:189], 0
	v_mfma_f32_16x16x32_bf16 v[22:25], v[158:161], v[186:189], 0
	v_mfma_f32_16x16x32_bf16 v[14:17], v[50:53], v[194:197], 0
	v_mfma_f32_16x16x32_bf16 v[6:9], v[158:161], v[194:197], 0
	v_mfma_f32_16x16x32_bf16 v[66:69], v[146:149], v[174:177], v[66:69]
	v_mfma_f32_16x16x32_bf16 v[58:61], v[166:169], v[174:177], v[58:61]
	v_mfma_f32_16x16x32_bf16 v[46:49], v[146:149], v[182:185], v[46:49]
	v_mfma_f32_16x16x32_bf16 v[38:41], v[166:169], v[182:185], v[38:41]
	v_mfma_f32_16x16x32_bf16 v[30:33], v[146:149], v[190:193], v[30:33]
	v_mfma_f32_16x16x32_bf16 v[22:25], v[166:169], v[190:193], v[22:25]
	v_mfma_f32_16x16x32_bf16 v[14:17], v[146:149], v[198:201], v[14:17]
	v_mfma_f32_16x16x32_bf16 v[6:9], v[166:169], v[198:201], v[6:9]
	s_barrier
	s_add_u32 s24, s28, 0x40000
	s_addc_u32 s25, s29, 0
	s_mov_b32 m0, s59
	s_nop 0
	global_load_lds_dwordx4 v0, s[24:25]
	s_mov_b32 m0, s62
	s_nop 0
	global_load_lds_dwordx4 v138, s[24:25]
	s_waitcnt vmcnt(6)
	s_barrier
	v_mfma_f32_16x16x32_bf16 v[54:57], v[210:213], v[170:173], 0
	v_mfma_f32_16x16x32_bf16 v[42:45], v[202:205], v[178:181], 0
	v_mfma_f32_16x16x32_bf16 v[34:37], v[210:213], v[178:181], 0
	v_mfma_f32_16x16x32_bf16 v[26:29], v[202:205], v[186:189], 0
	v_mfma_f32_16x16x32_bf16 v[18:21], v[210:213], v[186:189], 0
	v_mfma_f32_16x16x32_bf16 v[10:13], v[202:205], v[194:197], 0
	v_mfma_f32_16x16x32_bf16 v[2:5], v[210:213], v[194:197], 0
	v_mfma_f32_16x16x32_bf16 v[50:53], v[202:205], v[170:173], 0
	v_mfma_f32_16x16x32_bf16 v[54:57], v[214:217], v[174:177], v[54:57]
	v_mfma_f32_16x16x32_bf16 v[42:45], v[206:209], v[182:185], v[42:45]
	v_mfma_f32_16x16x32_bf16 v[34:37], v[214:217], v[182:185], v[34:37]
	v_mfma_f32_16x16x32_bf16 v[26:29], v[206:209], v[190:193], v[26:29]
	v_mfma_f32_16x16x32_bf16 v[18:21], v[214:217], v[190:193], v[18:21]
	v_mfma_f32_16x16x32_bf16 v[10:13], v[206:209], v[198:201], v[10:13]
	v_mfma_f32_16x16x32_bf16 v[2:5], v[214:217], v[198:201], v[2:5]
	v_mfma_f32_16x16x32_bf16 v[50:53], v[206:209], v[174:177], v[50:53]
	s_barrier
	s_branch .Lup605_p5
; #define PG8_STAGE(bufoff, gbase, voff) do { _Pragma("unroll") for (int _i = 0; _i < 2; ++_i) \
;     __builtin_amdgcn_global_load_lds((const unsigned*)((const char*)(gbase) + (voff)[_i]), (PG8_LAS unsigned*)(lds + (bufoff) + ldsw + _i * 8192), 16, 0, 0); } while (0)
; #define PG8_LDA(dst, b, h) do { _Pragma("unroll") for (int m = 0; m < 4; ++m) _Pragma("unroll") for (int k = 0; k < 2; ++k) dst[m][k] = *(const PG8_LAS bf16x8*)(lds + PG8_SA(b, h) + aoff + m * 2048 + k * 1024); } while (0)
; #define PG8_LDB(dst, b, h) do { _Pragma("unroll") for (int n = 0; n < 2; ++n) _Pragma("unroll") for (int k = 0; k < 2; ++k) dst[n][k] = *(const PG8_LAS bf16x8*)(lds + PG8_SB(b, h) + boff + n * 2048 + k * 1024); } while (0)
; #define PG8_MMA(ai, bj, At, Bt) do { __builtin_amdgcn_s_setprio(1); _Pragma("unroll") for (int m = 0; m < 4; ++m) _Pragma("unroll") for (int n = 0; n < 2; ++n) _Pragma("unroll") for (int k = 0; k < 2; ++k) \
;     acc[ai][bj][m][n] = __builtin_amdgcn_mfma_f32_16x16x32_bf16(Bt[n][k], At[m][k], acc[ai][bj][m][n], 0, 0, 0); __builtin_amdgcn_s_setprio(0); } while (0)
; #define PG8_WAIT_V(n) asm volatile("s_waitcnt vmcnt(" #n ")" ::: "memory")
; #define PG8_WAIT_L(n) asm volatile("s_waitcnt lgkmcnt(" #n ")" ::: "memory")
; #define PG8_BAR __builtin_amdgcn_s_barrier()
; template <class Epi>
; DI void gemm_phase(const bf16_t* __restrict__ gA, const bf16_t* __restrict__ gBt, int M, int N, int K, const Epi& E, char* lds_generic) {
;     ...
;     for (int t = 0; t < nt; t += 2) {
;       const bool last = (t == nt - 2);
;       const char* a1 = cA + (size_t)(t + 1) * kstep;
;       const char* a2 = last ? nA : cA + (size_t)(t + 2) * kstep; const char* b2 = last ? nB : cB + (size_t)(t + 2) * kstep;
;       const char* a3 = a2 + kstep; const char* b3 = b2 + kstep;
;       PG8_LDB(B0, 0, 0); PG8_SCHED; PG8_LDA(At, 0, 0); PG8_STAGE(PG8_SA(1, 1), a1 + hstep, voffA);
;       PG8_WAIT_L(8); PG8_BAR; PG8_WAIT_L(0); PG8_MMA(0, 0, At, B0); PG8_BAR; PG8_SCHED;
;       PG8_LDB(B1, 0, 1); PG8_STAGE(PG8_SB(0, 0), b2, voffB);
;       PG8_BAR; PG8_WAIT_L(0); PG8_MMA(0, 1, At, B1); PG8_BAR;
;       PG8_LDA(At, 0, 1); PG8_STAGE(PG8_SA(0, 0), a2, voffA);
;       PG8_BAR; PG8_WAIT_L(0); PG8_MMA(1, 0, At, B0); PG8_BAR; PG8_SCHED;
;       PG8_STAGE(PG8_SB(0, 1), b2 + hstep, voffB);
;       PG8_WAIT_V(6); PG8_BAR; PG8_MMA(1, 1, At, B1); PG8_BAR;
.LBB0_605:
	ds_read_b128 v[50:53], v155
	ds_read_b128 v[146:149], v155 offset:1024
	ds_read_b128 v[158:161], v155 offset:2048
	ds_read_b128 v[166:169], v155 offset:3072
	s_add_u32 s24, vcc_lo, 0xfffc0080
	s_addc_u32 s25, vcc_hi, -1
	s_cmp_eq_u32 s23, 12
	s_cselect_b32 s31, s20, s25
	s_cselect_b32 s30, s21, s24
	s_cselect_b32 s29, s27, s22
	s_cselect_b32 s28, s42, s87
	s_add_i32 m0, s72, 0xc000
	ds_read_b128 v[170:173], v154
	ds_read_b128 v[174:177], v154 offset:1024
	ds_read_b128 v[178:181], v154 offset:2048
	ds_read_b128 v[182:185], v154 offset:3072
	ds_read_b128 v[186:189], v154 offset:4096
	ds_read_b128 v[190:193], v154 offset:5120
	ds_read_b128 v[194:197], v154 offset:6144
	ds_read_b128 v[198:201], v154 offset:7168
	global_load_lds_dwordx4 v142, vcc
	s_add_i32 m0, s72, 0xe000
	s_nop 0
	global_load_lds_dwordx4 v144, vcc
	s_barrier
	s_waitcnt lgkmcnt(0)
	s_waitcnt lgkmcnt(0)
	v_mfma_f32_16x16x32_bf16 v[130:133], v[50:53], v[170:173], v[130:133]
	v_mfma_f32_16x16x32_bf16 v[122:125], v[158:161], v[170:173], v[122:125]
	v_mfma_f32_16x16x32_bf16 v[114:117], v[50:53], v[178:181], v[114:117]
	v_mfma_f32_16x16x32_bf16 v[106:109], v[158:161], v[178:181], v[106:109]
	v_mfma_f32_16x16x32_bf16 v[98:101], v[50:53], v[186:189], v[98:101]
	v_mfma_f32_16x16x32_bf16 v[90:93], v[158:161], v[186:189], v[90:93]
	v_mfma_f32_16x16x32_bf16 v[82:85], v[50:53], v[194:197], v[82:85]
	v_mfma_f32_16x16x32_bf16 v[74:77], v[158:161], v[194:197], v[74:77]
	v_mfma_f32_16x16x32_bf16 v[130:133], v[146:149], v[174:177], v[130:133]
	v_mfma_f32_16x16x32_bf16 v[122:125], v[166:169], v[174:177], v[122:125]
	v_mfma_f32_16x16x32_bf16 v[114:117], v[146:149], v[182:185], v[114:117]
	v_mfma_f32_16x16x32_bf16 v[106:109], v[166:169], v[182:185], v[106:109]
	v_mfma_f32_16x16x32_bf16 v[98:101], v[146:149], v[190:193], v[98:101]
	v_mfma_f32_16x16x32_bf16 v[90:93], v[166:169], v[190:193], v[90:93]
	v_mfma_f32_16x16x32_bf16 v[82:85], v[146:149], v[198:201], v[82:85]
	v_mfma_f32_16x16x32_bf16 v[74:77], v[166:169], v[198:201], v[74:77]
	s_barrier
	s_mov_b32 m0, s14
	ds_read_b128 v[202:205], v155 offset:16384
	ds_read_b128 v[206:209], v155 offset:17408
	ds_read_b128 v[210:213], v155 offset:18432
	ds_read_b128 v[214:217], v155 offset:19456
	global_load_lds_dwordx4 v0, s[28:29]
	s_mov_b32 m0, s15
	s_nop 0
	global_load_lds_dwordx4 v138, s[28:29]
	s_barrier
	s_waitcnt lgkmcnt(0)
	s_waitcnt lgkmcnt(0)
	v_mfma_f32_16x16x32_bf16 v[126:129], v[202:205], v[170:173], v[126:129]
	v_mfma_f32_16x16x32_bf16 v[118:121], v[210:213], v[170:173], v[118:121]
	v_mfma_f32_16x16x32_bf16 v[110:113], v[202:205], v[178:181], v[110:113]
	v_mfma_f32_16x16x32_bf16 v[102:105], v[210:213], v[178:181], v[102:105]
	v_mfma_f32_16x16x32_bf16 v[94:97], v[202:205], v[186:189], v[94:97]
	v_mfma_f32_16x16x32_bf16 v[86:89], v[210:213], v[186:189], v[86:89]
	v_mfma_f32_16x16x32_bf16 v[78:81], v[202:205], v[194:197], v[78:81]
	v_mfma_f32_16x16x32_bf16 v[70:73], v[210:213], v[194:197], v[70:73]
	v_mfma_f32_16x16x32_bf16 v[126:129], v[206:209], v[174:177], v[126:129]
	v_mfma_f32_16x16x32_bf16 v[118:121], v[214:217], v[174:177], v[118:121]
	v_mfma_f32_16x16x32_bf16 v[110:113], v[206:209], v[182:185], v[110:113]
	v_mfma_f32_16x16x32_bf16 v[102:105], v[214:217], v[182:185], v[102:105]
	v_mfma_f32_16x16x32_bf16 v[94:97], v[206:209], v[190:193], v[94:97]
	v_mfma_f32_16x16x32_bf16 v[86:89], v[214:217], v[190:193], v[86:89]
	v_mfma_f32_16x16x32_bf16 v[78:81], v[206:209], v[198:201], v[78:81]
	v_mfma_f32_16x16x32_bf16 v[70:73], v[214:217], v[198:201], v[70:73]
	s_mov_b32 m0, s72
	s_barrier
	ds_read_b128 v[170:173], v154 offset:16384
	ds_read_b128 v[174:177], v154 offset:17408
	ds_read_b128 v[178:181], v154 offset:18432
	ds_read_b128 v[182:185], v154 offset:19456
	ds_read_b128 v[186:189], v154 offset:20480
	ds_read_b128 v[190:193], v154 offset:21504
	ds_read_b128 v[194:197], v154 offset:22528
	ds_read_b128 v[198:201], v154 offset:23552
	global_load_lds_dwordx4 v134, s[30:31]
	s_mov_b32 m0, s58
	s_nop 0
	global_load_lds_dwordx4 v136, s[30:31]
	s_barrier
	s_waitcnt lgkmcnt(0)
	s_waitcnt lgkmcnt(0)
	v_mfma_f32_16x16x32_bf16 v[66:69], v[50:53], v[170:173], v[66:69]
	v_mfma_f32_16x16x32_bf16 v[58:61], v[158:161], v[170:173], v[58:61]
	v_mfma_f32_16x16x32_bf16 v[46:49], v[50:53], v[178:181], v[46:49]
	v_mfma_f32_16x16x32_bf16 v[38:41], v[158:161], v[178:181], v[38:41]
	v_mfma_f32_16x16x32_bf16 v[30:33], v[50:53], v[186:189], v[30:33]
	v_mfma_f32_16x16x32_bf16 v[22:25], v[158:161], v[186:189], v[22:25]
	v_mfma_f32_16x16x32_bf16 v[14:17], v[50:53], v[194:197], v[14:17]
	v_mfma_f32_16x16x32_bf16 v[6:9], v[158:161], v[194:197], v[6:9]
	v_mfma_f32_16x16x32_bf16 v[66:69], v[146:149], v[174:177], v[66:69]
	v_mfma_f32_16x16x32_bf16 v[58:61], v[166:169], v[174:177], v[58:61]
	v_mfma_f32_16x16x32_bf16 v[46:49], v[146:149], v[182:185], v[46:49]
	v_mfma_f32_16x16x32_bf16 v[38:41], v[166:169], v[182:185], v[38:41]
	v_mfma_f32_16x16x32_bf16 v[30:33], v[146:149], v[190:193], v[30:33]
	v_mfma_f32_16x16x32_bf16 v[22:25], v[166:169], v[190:193], v[22:25]
	v_mfma_f32_16x16x32_bf16 v[14:17], v[146:149], v[198:201], v[14:17]
	v_mfma_f32_16x16x32_bf16 v[6:9], v[166:169], v[198:201], v[6:9]
	s_barrier
	s_add_u32 s24, s28, 0x40000
	s_addc_u32 s25, s29, 0
	s_mov_b32 m0, s59
	s_nop 0
	global_load_lds_dwordx4 v0, s[24:25]
	s_mov_b32 m0, s62
	s_nop 0
	global_load_lds_dwordx4 v138, s[24:25]
	s_waitcnt vmcnt(6)
	s_barrier
	v_mfma_f32_16x16x32_bf16 v[54:57], v[210:213], v[170:173], v[54:57]
	v_mfma_f32_16x16x32_bf16 v[42:45], v[202:205], v[178:181], v[42:45]
	v_mfma_f32_16x16x32_bf16 v[34:37], v[210:213], v[178:181], v[34:37]
	v_mfma_f32_16x16x32_bf16 v[26:29], v[202:205], v[186:189], v[26:29]
	v_mfma_f32_16x16x32_bf16 v[18:21], v[210:213], v[186:189], v[18:21]
	v_mfma_f32_16x16x32_bf16 v[10:13], v[202:205], v[194:197], v[10:13]
	v_mfma_f32_16x16x32_bf16 v[2:5], v[210:213], v[194:197], v[2:5]
	v_mfma_f32_16x16x32_bf16 v[50:53], v[202:205], v[170:173], v[62:65]
	v_mfma_f32_16x16x32_bf16 v[54:57], v[214:217], v[174:177], v[54:57]
	v_mfma_f32_16x16x32_bf16 v[42:45], v[206:209], v[182:185], v[42:45]
	v_mfma_f32_16x16x32_bf16 v[34:37], v[214:217], v[182:185], v[34:37]
	v_mfma_f32_16x16x32_bf16 v[26:29], v[206:209], v[190:193], v[26:29]
	v_mfma_f32_16x16x32_bf16 v[18:21], v[214:217], v[190:193], v[18:21]
	v_mfma_f32_16x16x32_bf16 v[10:13], v[206:209], v[198:201], v[10:13]
	v_mfma_f32_16x16x32_bf16 v[2:5], v[214:217], v[198:201], v[2:5]
	v_mfma_f32_16x16x32_bf16 v[50:53], v[206:209], v[174:177], v[50:53]
	s_barrier
; #define PG8_STAGE(bufoff, gbase, voff) do { _Pragma("unroll") for (int _i = 0; _i < 2; ++_i) \
;     __builtin_amdgcn_global_load_lds((const unsigned*)((const char*)(gbase) + (voff)[_i]), (PG8_LAS unsigned*)(lds + (bufoff) + ldsw + _i * 8192), 16, 0, 0); } while (0)
; #define PG8_LDA(dst, b, h) do { _Pragma("unroll") for (int m = 0; m < 4; ++m) _Pragma("unroll") for (int k = 0; k < 2; ++k) dst[m][k] = *(const PG8_LAS bf16x8*)(lds + PG8_SA(b, h) + aoff + m * 2048 + k * 1024); } while (0)
; #define PG8_LDB(dst, b, h) do { _Pragma("unroll") for (int n = 0; n < 2; ++n) _Pragma("unroll") for (int k = 0; k < 2; ++k) dst[n][k] = *(const PG8_LAS bf16x8*)(lds + PG8_SB(b, h) + boff + n * 2048 + k * 1024); } while (0)
; #define PG8_MMA(ai, bj, At, Bt) do { __builtin_amdgcn_s_setprio(1); _Pragma("unroll") for (int m = 0; m < 4; ++m) _Pragma("unroll") for (int n = 0; n < 2; ++n) _Pragma("unroll") for (int k = 0; k < 2; ++k) \
;     acc[ai][bj][m][n] = __builtin_amdgcn_mfma_f32_16x16x32_bf16(Bt[n][k], At[m][k], acc[ai][bj][m][n], 0, 0, 0); __builtin_amdgcn_s_setprio(0); } while (0)
; #define PG8_WAIT_V(n) asm volatile("s_waitcnt vmcnt(" #n ")" ::: "memory")
; #define PG8_WAIT_L(n) asm volatile("s_waitcnt lgkmcnt(" #n ")" ::: "memory")
; #define PG8_BAR __builtin_amdgcn_s_barrier()
; #define PG8_SCHED __builtin_amdgcn_sched_barrier(0)
; template <class Epi>
; DI void gemm_phase(const bf16_t* __restrict__ gA, const bf16_t* __restrict__ gBt, int M, int N, int K, const Epi& E, char* lds_generic) {
;     ...
;       PG8_LDB(B0, 1, 0); PG8_SCHED; PG8_LDA(At, 1, 0); PG8_STAGE(PG8_SA(0, 1), a2 + hstep, voffA);
;       PG8_WAIT_L(8); PG8_BAR; PG8_WAIT_L(0); PG8_MMA(0, 0, At, B0); PG8_BAR; PG8_SCHED;
;       PG8_LDB(B1, 1, 1); PG8_STAGE(PG8_SB(1, 0), b3, voffB);
;       PG8_BAR; PG8_WAIT_L(0); PG8_MMA(0, 1, At, B1); PG8_BAR;
;       PG8_LDA(At, 1, 1); PG8_STAGE(PG8_SA(1, 0), a3, voffA);
;       PG8_BAR; PG8_WAIT_L(0); PG8_MMA(1, 0, At, B0); PG8_BAR; PG8_SCHED;
;       PG8_STAGE(PG8_SB(1, 1), b3 + hstep, voffB);
;       PG8_WAIT_V(6); PG8_BAR; PG8_MMA(1, 1, At, B1); PG8_BAR;
.Lup605_p5:
	ds_read_b128 v[62:65], v155 offset:32768
	ds_read_b128 v[146:149], v155 offset:33792
	ds_read_b128 v[158:161], v155 offset:34816
	ds_read_b128 v[166:169], v155 offset:35840
	s_add_u32 s24, s30, 0x40000
	s_addc_u32 s25, s31, 0
	s_mov_b32 m0, s7
	ds_read_b128 v[170:173], v154 offset:32768
	ds_read_b128 v[174:177], v154 offset:33792
	ds_read_b128 v[178:181], v154 offset:34816
	ds_read_b128 v[182:185], v154 offset:35840
	ds_read_b128 v[186:189], v154 offset:36864
	ds_read_b128 v[190:193], v154 offset:37888
	ds_read_b128 v[194:197], v154 offset:38912
	ds_read_b128 v[198:201], v154 offset:39936
	global_load_lds_dwordx4 v134, s[24:25]
	s_mov_b32 m0, s12
	s_nop 0
	global_load_lds_dwordx4 v136, s[24:25]
	s_barrier
	s_waitcnt lgkmcnt(0)
	s_waitcnt lgkmcnt(0)
	v_mfma_f32_16x16x32_bf16 v[130:133], v[62:65], v[170:173], v[130:133]
	v_mfma_f32_16x16x32_bf16 v[122:125], v[158:161], v[170:173], v[122:125]
	v_mfma_f32_16x16x32_bf16 v[114:117], v[62:65], v[178:181], v[114:117]
	v_mfma_f32_16x16x32_bf16 v[106:109], v[158:161], v[178:181], v[106:109]
	v_mfma_f32_16x16x32_bf16 v[98:101], v[62:65], v[186:189], v[98:101]
	v_mfma_f32_16x16x32_bf16 v[90:93], v[158:161], v[186:189], v[90:93]
	v_mfma_f32_16x16x32_bf16 v[82:85], v[62:65], v[194:197], v[82:85]
	v_mfma_f32_16x16x32_bf16 v[74:77], v[158:161], v[194:197], v[74:77]
	v_mfma_f32_16x16x32_bf16 v[130:133], v[146:149], v[174:177], v[130:133]
	v_mfma_f32_16x16x32_bf16 v[122:125], v[166:169], v[174:177], v[122:125]
	v_mfma_f32_16x16x32_bf16 v[114:117], v[146:149], v[182:185], v[114:117]
	v_mfma_f32_16x16x32_bf16 v[106:109], v[166:169], v[182:185], v[106:109]
	v_mfma_f32_16x16x32_bf16 v[98:101], v[146:149], v[190:193], v[98:101]
	v_mfma_f32_16x16x32_bf16 v[90:93], v[166:169], v[190:193], v[90:93]
	v_mfma_f32_16x16x32_bf16 v[82:85], v[146:149], v[198:201], v[82:85]
	v_mfma_f32_16x16x32_bf16 v[74:77], v[166:169], v[198:201], v[74:77]
	s_barrier
	s_mov_b32 m0, s13
	ds_read_b128 v[202:205], v155 offset:49152
	ds_read_b128 v[206:209], v155 offset:50176
	ds_read_b128 v[210:213], v155 offset:51200
	ds_read_b128 v[214:217], v155 offset:52224
	s_add_u32 s24, s28, 0x80
	s_addc_u32 s25, s29, 0
	global_load_lds_dwordx4 v0, s[24:25]
	s_mov_b32 m0, s35
	s_nop 0
	s_add_u32 s24, s28, 0x80
	s_addc_u32 s25, s29, 0
	global_load_lds_dwordx4 v138, s[24:25]
	s_barrier
	s_waitcnt lgkmcnt(0)
	s_waitcnt lgkmcnt(0)
	v_mfma_f32_16x16x32_bf16 v[126:129], v[202:205], v[170:173], v[126:129]
	v_mfma_f32_16x16x32_bf16 v[118:121], v[210:213], v[170:173], v[118:121]
	v_mfma_f32_16x16x32_bf16 v[110:113], v[202:205], v[178:181], v[110:113]
	v_mfma_f32_16x16x32_bf16 v[102:105], v[210:213], v[178:181], v[102:105]
	v_mfma_f32_16x16x32_bf16 v[94:97], v[202:205], v[186:189], v[94:97]
	v_mfma_f32_16x16x32_bf16 v[86:89], v[210:213], v[186:189], v[86:89]
	v_mfma_f32_16x16x32_bf16 v[78:81], v[202:205], v[194:197], v[78:81]
	v_mfma_f32_16x16x32_bf16 v[70:73], v[210:213], v[194:197], v[70:73]
	v_mfma_f32_16x16x32_bf16 v[126:129], v[206:209], v[174:177], v[126:129]
	v_mfma_f32_16x16x32_bf16 v[118:121], v[214:217], v[174:177], v[118:121]
	v_mfma_f32_16x16x32_bf16 v[110:113], v[206:209], v[182:185], v[110:113]
	v_mfma_f32_16x16x32_bf16 v[102:105], v[214:217], v[182:185], v[102:105]
	v_mfma_f32_16x16x32_bf16 v[94:97], v[206:209], v[190:193], v[94:97]
	v_mfma_f32_16x16x32_bf16 v[86:89], v[214:217], v[190:193], v[86:89]
	v_mfma_f32_16x16x32_bf16 v[78:81], v[206:209], v[198:201], v[78:81]
	v_mfma_f32_16x16x32_bf16 v[70:73], v[214:217], v[198:201], v[70:73]
	s_mov_b32 m0, s53
	s_barrier
; #define PG8_STAGE(bufoff, gbase, voff) do { _Pragma("unroll") for (int _i = 0; _i < 2; ++_i) \
;     __builtin_amdgcn_global_load_lds((const unsigned*)((const char*)(gbase) + (voff)[_i]), (PG8_LAS unsigned*)(lds + (bufoff) + ldsw + _i * 8192), 16, 0, 0); } while (0)
; #define PG8_LDA(dst, b, h) do { _Pragma("unroll") for (int m = 0; m < 4; ++m) _Pragma("unroll") for (int k = 0; k < 2; ++k) dst[m][k] = *(const PG8_LAS bf16x8*)(lds + PG8_SA(b, h) + aoff + m * 2048 + k * 1024); } while (0)
; #define PG8_MMA(ai, bj, At, Bt) do { __builtin_amdgcn_s_setprio(1); _Pragma("unroll") for (int m = 0; m < 4; ++m) _Pragma("unroll") for (int n = 0; n < 2; ++n) _Pragma("unroll") for (int k = 0; k < 2; ++k) \
;     acc[ai][bj][m][n] = __builtin_amdgcn_mfma_f32_16x16x32_bf16(Bt[n][k], At[m][k], acc[ai][bj][m][n], 0, 0, 0); __builtin_amdgcn_s_setprio(0); } while (0)
; #define PG8_WAIT_V(n) asm volatile("s_waitcnt vmcnt(" #n ")" ::: "memory")
; #define PG8_WAIT_L(n) asm volatile("s_waitcnt lgkmcnt(" #n ")" ::: "memory")
; #define PG8_BAR __builtin_amdgcn_s_barrier()
; #define PG8_SCHED __builtin_amdgcn_sched_barrier(0)
; #define PG8_RTAB_LOAD(var, unit) do { if constexpr (Epi::NEEDS_R) { var = *(const uint4*)(E.ssq + (size_t)((unit).pm * BM + (tid >> 1)) * 16 + (tid & 1) * 8); } } while (0)
; template <class Epi>
; DI void gemm_phase(const bf16_t* __restrict__ gA, const bf16_t* __restrict__ gBt, int M, int N, int K, const Epi& E, char* lds_generic) {
;     ...
;       PG8_LDA(At, 1, 1); PG8_STAGE(PG8_SA(1, 0), a3, voffA);
;       PG8_BAR; PG8_WAIT_L(0); PG8_MMA(1, 0, At, B0); PG8_BAR; PG8_SCHED;
;       PG8_STAGE(PG8_SB(1, 1), b3 + hstep, voffB);
;       PG8_WAIT_V(6); PG8_BAR; PG8_MMA(1, 1, At, B1); PG8_BAR;
;     }
;     uint4 rtn_ = {0u, 0u, 0u, 0u};
;     if (has_next) PG8_RTAB_LOAD(rtn_, nxt);
	ds_read_b128 v[170:173], v154 offset:49152
	ds_read_b128 v[174:177], v154 offset:50176
	ds_read_b128 v[178:181], v154 offset:51200
	ds_read_b128 v[182:185], v154 offset:52224
	ds_read_b128 v[186:189], v154 offset:53248
	ds_read_b128 v[190:193], v154 offset:54272
	ds_read_b128 v[194:197], v154 offset:55296
	ds_read_b128 v[198:201], v154 offset:56320
	s_add_u32 s24, s30, 0x80
	s_addc_u32 s25, s31, 0
	global_load_lds_dwordx4 v134, s[24:25]
	s_mov_b32 m0, s74
	s_nop 0
	s_add_u32 s24, s30, 0x80
	s_addc_u32 s25, s31, 0
	global_load_lds_dwordx4 v136, s[24:25]
	s_barrier
	s_waitcnt lgkmcnt(0)
	s_waitcnt lgkmcnt(0)
	v_mfma_f32_16x16x32_bf16 v[66:69], v[62:65], v[170:173], v[66:69]
	v_mfma_f32_16x16x32_bf16 v[58:61], v[158:161], v[170:173], v[58:61]
	v_mfma_f32_16x16x32_bf16 v[46:49], v[62:65], v[178:181], v[46:49]
	v_mfma_f32_16x16x32_bf16 v[38:41], v[158:161], v[178:181], v[38:41]
	v_mfma_f32_16x16x32_bf16 v[30:33], v[62:65], v[186:189], v[30:33]
	v_mfma_f32_16x16x32_bf16 v[22:25], v[158:161], v[186:189], v[22:25]
	v_mfma_f32_16x16x32_bf16 v[14:17], v[62:65], v[194:197], v[14:17]
	v_mfma_f32_16x16x32_bf16 v[6:9], v[158:161], v[194:197], v[6:9]
	v_mfma_f32_16x16x32_bf16 v[66:69], v[146:149], v[174:177], v[66:69]
	v_mfma_f32_16x16x32_bf16 v[58:61], v[166:169], v[174:177], v[58:61]
	v_mfma_f32_16x16x32_bf16 v[46:49], v[146:149], v[182:185], v[46:49]
	v_mfma_f32_16x16x32_bf16 v[38:41], v[166:169], v[182:185], v[38:41]
	v_mfma_f32_16x16x32_bf16 v[30:33], v[146:149], v[190:193], v[30:33]
	v_mfma_f32_16x16x32_bf16 v[22:25], v[166:169], v[190:193], v[22:25]
	v_mfma_f32_16x16x32_bf16 v[14:17], v[146:149], v[198:201], v[14:17]
	v_mfma_f32_16x16x32_bf16 v[6:9], v[166:169], v[198:201], v[6:9]
	s_barrier
	s_add_u32 s24, s28, 0x40080
	s_addc_u32 s25, s29, 0
	s_mov_b32 m0, s60
	s_nop 0
	global_load_lds_dwordx4 v0, s[24:25]
	s_mov_b32 m0, s6
	s_nop 0
	global_load_lds_dwordx4 v138, s[24:25]
	s_waitcnt vmcnt(6)
	s_barrier
	v_mfma_f32_16x16x32_bf16 v[50:53], v[202:205], v[170:173], v[50:53]
	v_mfma_f32_16x16x32_bf16 v[62:65], v[206:209], v[174:177], v[50:53]
	v_mfma_f32_16x16x32_bf16 v[50:53], v[210:213], v[170:173], v[54:57]
	v_mfma_f32_16x16x32_bf16 v[42:45], v[202:205], v[178:181], v[42:45]
	v_mfma_f32_16x16x32_bf16 v[34:37], v[210:213], v[178:181], v[34:37]
	v_mfma_f32_16x16x32_bf16 v[26:29], v[202:205], v[186:189], v[26:29]
	v_mfma_f32_16x16x32_bf16 v[18:21], v[210:213], v[186:189], v[18:21]
	v_mfma_f32_16x16x32_bf16 v[10:13], v[202:205], v[194:197], v[10:13]
	v_mfma_f32_16x16x32_bf16 v[2:5], v[210:213], v[194:197], v[2:5]
	v_mfma_f32_16x16x32_bf16 v[54:57], v[214:217], v[174:177], v[50:53]
	v_mfma_f32_16x16x32_bf16 v[42:45], v[206:209], v[182:185], v[42:45]
	v_mfma_f32_16x16x32_bf16 v[34:37], v[214:217], v[182:185], v[34:37]
	v_mfma_f32_16x16x32_bf16 v[26:29], v[206:209], v[190:193], v[26:29]
	v_mfma_f32_16x16x32_bf16 v[18:21], v[214:217], v[190:193], v[18:21]
	v_mfma_f32_16x16x32_bf16 v[10:13], v[206:209], v[198:201], v[10:13]
	v_mfma_f32_16x16x32_bf16 v[2:5], v[214:217], v[198:201], v[2:5]
	s_add_i32 s23, s23, 2
	s_add_u32 vcc_lo, vcc_lo, 0x100
	s_addc_u32 vcc_hi, vcc_hi, 0
	s_add_u32 s87, s87, 0x100
	s_addc_u32 s22, s22, 0
	s_cmp_gt_u32 s23, 13
	s_barrier
	s_cbranch_scc0 .LBB0_605
	v_mov_b32_e32 v50, 0
	s_and_b64 vcc, exec, s[38:39]
	v_mov_b32_e32 v51, 0
	v_mov_b32_e32 v52, 0
	v_mov_b32_e32 v53, 0
	s_cbranch_vccz .LBB0_608
	v_lshl_add_u32 v50, s86, 8, v150
	v_ashrrev_i32_e32 v51, 31, v50
	v_lshlrev_b64 v[50:51], 5, v[50:51]
	v_lshl_add_u64 v[50:51], v[140:141], 0, v[50:51]
	global_load_dwordx4 v[50:53], v[50:51], off

; DI float bflo(unsigned u) { return __uint_as_float(u << 16); }
; DI float bfhi(unsigned u) { return __uint_as_float(u & 0xffff0000u); }
;   DI void init(f32x4 (&acc)[2][2][4][2], const Unit&, int, int, int, int) const { acc_zero(acc); }
; #define PG8_BAR __builtin_amdgcn_s_barrier()
;   DI void init(f32x4 (&acc)[2][2][4][2], const Unit& u, int wr, int wc, int fr, int fq) const {
;     const int row0 = u.pm * BM + wr * 64 + fr, col0 = u.pn * BM + wc * 32 + 8 * fq; const float ic = 1.f / coef;
; #pragma unroll
;     for (int ai = 0; ai < 2; ++ai)
; #pragma unroll
;       for (int m = 0; m < 4; ++m) { const bf16_t* rowp = src + (size_t)(row0 + ai * HALF + m * 16) * DM + col0;
; #pragma unroll
;         for (int bj = 0; bj < 2; ++bj) { const u32x4 w = *(const u32x4*)(rowp + bj * HALF);
;           acc[ai][bj][m][0] = (f32x4){bflo(w.x), bfhi(w.x), bflo(w.y), bfhi(w.y)} * ic; acc[ai][bj][m][1] = (f32x4){bflo(w.z), bfhi(w.z), bflo(w.w), bfhi(w.w)} * ic; } }
; template <class Epi>
; DI void gemm_phase(const bf16_t* __restrict__ gA, const bf16_t* __restrict__ gBt, int M, int N, int K, const Epi& E, char* lds_generic) {
;     ...
;   for (int i = 0; i < 2; ++i) { int R, C; stage_rc(tid * 16 + i * 8192, R, C); const int Rb = Epi::PERM ? ((R & ~31) + perm32(R & 31)) : R;
;     voffA[i] = (unsigned)(R * K + C) * 2u; voffB[i] = (unsigned)(Rb * K + C) * 2u; }
;   const size_t kstep = (size_t)(BK * 2);
;   const size_t hstep = (size_t)HALF * K * 2;
;   const size_t tstep = 2 * hstep;
;   const unsigned ldsw = (unsigned)wid * 1024u;
;   const int aoff = lds_byte(wr * 64 + fr, fq * 8), boff = lds_byte(wc * 32 + fr, fq * 8);
;     ...
;   Unit cur, nxt; int ui = 0;
;   if (!S.next(0, cur)) return;
;   f32x4 acc[2][2][4][2];
;   E.init(acc, cur, wr, wc, fr, fq);
;     ...
;   { uint4 rt0_ = {0u, 0u, 0u, 0u}; PG8_RTAB_LOAD(rt0_, cur); PG8_RTAB_FIN(rt0_, 0); }
;   bf16x8 At[4][2], B0[2][2], B1[2][2];
;   const char* cA = (const char*)gA + (size_t)cur.pm * tstep; const char* cB = (const char*)gBt + (size_t)cur.pn * tstep;
;   PG8_STAGE(PG8_SB(0, 0), cB, voffB); PG8_STAGE(PG8_SA(0, 0), cA, voffA); PG8_STAGE(PG8_SB(0, 1), cB + hstep, voffB); PG8_STAGE(PG8_SA(0, 1), cA + hstep, voffA);
;   if (wr == 1) PG8_BAR;
;   PG8_WAIT_V(4); PG8_BAR;
;   PG8_STAGE(PG8_SB(1, 0), cB + kstep, voffB); PG8_STAGE(PG8_SA(1, 0), cA + kstep, voffA); PG8_STAGE(PG8_SB(1, 1), cB + hstep + kstep, voffB);
;   PG8_WAIT_V(6); PG8_BAR;
.LBB0_671:
	s_lshl_b64 s[20:21], s[26:27], 1
	v_readlane_b32 s19, v255, 58
	s_add_u32 s26, s19, s20
	v_readlane_b32 s19, v255, 56
	s_waitcnt vmcnt(0)
	v_lshlrev_b32_e32 v118, 16, v54
	v_and_b32_e32 v119, 0xffff0000, v54
	v_lshlrev_b32_e32 v120, 16, v55
	v_and_b32_e32 v121, 0xffff0000, v55
	v_lshlrev_b32_e32 v114, 16, v56
	v_and_b32_e32 v115, 0xffff0000, v56
	v_lshlrev_b32_e32 v116, 16, v57
	v_and_b32_e32 v117, 0xffff0000, v57
	v_lshlrev_b32_e32 v54, 16, v26
	v_and_b32_e32 v55, 0xffff0000, v26
	v_lshlrev_b32_e32 v56, 16, v27
	v_and_b32_e32 v57, 0xffff0000, v27
	v_lshl_add_u64 v[26:27], s[90:91], 0, v[0:1]
	v_mov_b32_e32 v135, v1
	s_addc_u32 s27, s19, s21
	s_add_i32 s59, s12, 0x18000
	v_lshlrev_b32_e32 v94, 16, v50
	v_and_b32_e32 v95, 0xffff0000, v50
	v_lshlrev_b32_e32 v96, 16, v51
	v_and_b32_e32 v97, 0xffff0000, v51
	v_lshlrev_b32_e32 v90, 16, v52
	v_and_b32_e32 v91, 0xffff0000, v52
	v_lshlrev_b32_e32 v92, 16, v53
	v_and_b32_e32 v93, 0xffff0000, v53
	v_lshlrev_b32_e32 v50, 16, v28
	v_and_b32_e32 v51, 0xffff0000, v28
	v_lshlrev_b32_e32 v52, 16, v29
	v_and_b32_e32 v53, 0xffff0000, v29
	v_lshl_add_u64 v[28:29], s[90:91], 0, v[134:135]
	v_mov_b32_e32 v131, v1
	v_lshl_add_u64 v[26:27], v[26:27], 0, s[10:11]
	s_mov_b32 m0, s59
	s_add_i32 s60, s12, 0x1a000
	v_lshlrev_b32_e32 v70, 16, v30
	v_and_b32_e32 v71, 0xffff0000, v30
	v_lshlrev_b32_e32 v72, 16, v31
	v_and_b32_e32 v73, 0xffff0000, v31
	v_lshl_add_u64 v[30:31], s[88:89], 0, v[130:131]
	v_mov_b32_e32 v133, v1
	s_lshl_b32 s8, s8, 13
	s_lshl_b32 s22, s7, 12
	global_load_lds_dwordx4 v[26:27], off
	v_lshl_add_u64 v[26:27], v[28:29], 0, s[10:11]
	s_mov_b32 m0, s60
	s_add_i32 s62, s12, 0x8000
	s_add_i32 s72, s12, 0xa000
	v_lshlrev_b32_e32 v66, 16, v32
	v_and_b32_e32 v67, 0xffff0000, v32
	v_lshlrev_b32_e32 v68, 16, v33
	v_and_b32_e32 v69, 0xffff0000, v33
	v_lshl_add_u64 v[32:33], s[88:89], 0, v[132:133]
	global_load_lds_dwordx4 v[26:27], off
	v_lshl_add_u64 v[26:27], v[30:31], 0, s[10:11]
	s_mov_b32 m0, s62
	s_add_u32 s20, s90, 0xb0080
	global_load_lds_dwordx4 v[26:27], off
	v_lshl_add_u64 v[26:27], v[32:33], 0, s[10:11]
	s_mov_b32 m0, s72
	s_addc_u32 s21, s91, 0
	s_add_i32 s74, s12, 0x1c000
	global_load_lds_dwordx4 v[26:27], off
	v_lshl_add_u64 v[26:27], s[20:21], 0, v[0:1]
	s_mov_b32 m0, s74
	s_add_i32 s19, s12, 0x1e000
	global_load_lds_dwordx4 v[26:27], off
	v_lshl_add_u64 v[26:27], s[20:21], 0, v[134:135]
	s_mov_b32 m0, s19
	v_or_b32_e32 v144, s1, v146
	global_load_lds_dwordx4 v[26:27], off
	s_waitcnt vmcnt(10)
	s_barrier
	v_lshlrev_b32_e32 v145, 6, v144
	v_lshlrev_b32_e32 v149, 4, v136
	s_movk_i32 s1, 0x3c0
	v_lshlrev_b32_e32 v150, 2, v144
	v_and_or_b32 v145, v145, s1, v149
	v_and_b32_e32 v150, 32, v150
	v_bitop3_b32 v145, v145, s8, v150 bitop3:0xde
	s_movk_i32 s8, 0xb00
	v_cmp_eq_u32_e64 s[36:37], 0, v136
	v_lshrrev_b32_e32 v137, 1, v137
	v_mul_lo_u32 v136, v139, s8
	s_mov_b32 s20, 0xb000
	v_or_b32_e32 v147, s0, v147
	v_mad_u64_u32 v[136:137], s[0:1], v137, s20, v[136:137]
	v_or_b32_e32 v136, v136, v138
	v_lshrrev_b32_e32 v139, 1, v141
	v_mul_lo_u32 v138, v143, s8
	v_lshl_or_b32 v149, v146, 6, v149
	v_lshlrev_b32_e32 v146, 2, v146
	v_mad_u64_u32 v[138:139], s[0:1], v139, s20, v[138:139]
	v_and_b32_e32 v146, 32, v146
	s_waitcnt vmcnt(6)
	v_or_b32_e32 v138, v138, v142
	v_bitop3_b32 v146, v149, s22, v146 bitop3:0xde
	v_add_u32_e32 v146, 0x10000, v146
	v_add_lshl_u32 v136, v136, v140, 1
	v_mov_b32_e32 v137, v1
	s_mov_b64 s[22:23], 0xb0080
	v_add_lshl_u32 v138, v138, v148, 1
	v_mov_b32_e32 v139, v1
	v_lshlrev_b32_e32 v126, 16, v62
	v_and_b32_e32 v127, 0xffff0000, v62
	v_lshlrev_b32_e32 v128, 16, v63
	v_and_b32_e32 v129, 0xffff0000, v63
	v_lshlrev_b32_e32 v122, 16, v64
	v_and_b32_e32 v123, 0xffff0000, v64
	v_lshlrev_b32_e32 v124, 16, v65
	v_and_b32_e32 v125, 0xffff0000, v65
	v_lshlrev_b32_e32 v110, 16, v58
	v_and_b32_e32 v111, 0xffff0000, v58
	v_lshlrev_b32_e32 v112, 16, v59
	v_and_b32_e32 v113, 0xffff0000, v59
	v_lshlrev_b32_e32 v106, 16, v60
	v_and_b32_e32 v107, 0xffff0000, v60
	v_lshlrev_b32_e32 v108, 16, v61
	v_and_b32_e32 v109, 0xffff0000, v61
	v_lshlrev_b32_e32 v102, 16, v46
	v_and_b32_e32 v103, 0xffff0000, v46
	v_lshlrev_b32_e32 v104, 16, v47
	v_and_b32_e32 v105, 0xffff0000, v47
	v_lshlrev_b32_e32 v98, 16, v48
	v_and_b32_e32 v99, 0xffff0000, v48
	v_lshlrev_b32_e32 v100, 16, v49
	v_and_b32_e32 v101, 0xffff0000, v49
	v_lshlrev_b32_e32 v86, 16, v38
	v_and_b32_e32 v87, 0xffff0000, v38
	v_lshlrev_b32_e32 v88, 16, v39
	v_and_b32_e32 v89, 0xffff0000, v39
	v_lshlrev_b32_e32 v82, 16, v40
	v_and_b32_e32 v83, 0xffff0000, v40
	v_lshlrev_b32_e32 v84, 16, v41
	v_and_b32_e32 v85, 0xffff0000, v41
	v_lshlrev_b32_e32 v78, 16, v42
	v_and_b32_e32 v79, 0xffff0000, v42
	v_lshlrev_b32_e32 v80, 16, v43
	v_and_b32_e32 v81, 0xffff0000, v43
	v_lshlrev_b32_e32 v74, 16, v44
	v_and_b32_e32 v75, 0xffff0000, v44
	v_lshlrev_b32_e32 v76, 16, v45
	v_and_b32_e32 v77, 0xffff0000, v45
	v_lshlrev_b32_e32 v62, 16, v34
	v_and_b32_e32 v63, 0xffff0000, v34
	v_lshlrev_b32_e32 v64, 16, v35
	v_and_b32_e32 v65, 0xffff0000, v35
	v_lshlrev_b32_e32 v58, 16, v36
	v_and_b32_e32 v59, 0xffff0000, v36
	v_lshlrev_b32_e32 v60, 16, v37
	v_and_b32_e32 v61, 0xffff0000, v37
	v_lshlrev_b32_e32 v46, 16, v22
	v_and_b32_e32 v47, 0xffff0000, v22
	v_lshlrev_b32_e32 v48, 16, v23
	v_and_b32_e32 v49, 0xffff0000, v23
	v_lshlrev_b32_e32 v42, 16, v24
	v_and_b32_e32 v43, 0xffff0000, v24
	v_lshlrev_b32_e32 v44, 16, v25
	v_and_b32_e32 v45, 0xffff0000, v25
	v_lshlrev_b32_e32 v38, 16, v14
	v_and_b32_e32 v39, 0xffff0000, v14
	v_lshlrev_b32_e32 v40, 16, v15
	v_and_b32_e32 v41, 0xffff0000, v15
	v_lshlrev_b32_e32 v34, 16, v16
	v_and_b32_e32 v35, 0xffff0000, v16
	v_lshlrev_b32_e32 v36, 16, v17
	v_and_b32_e32 v37, 0xffff0000, v17
	v_lshlrev_b32_e32 v30, 16, v18
	v_and_b32_e32 v31, 0xffff0000, v18
	v_lshlrev_b32_e32 v32, 16, v19
	v_and_b32_e32 v33, 0xffff0000, v19
	v_lshlrev_b32_e32 v26, 16, v20
	v_and_b32_e32 v27, 0xffff0000, v20
	v_lshlrev_b32_e32 v28, 16, v21
	v_and_b32_e32 v29, 0xffff0000, v21
	v_lshlrev_b32_e32 v22, 16, v6
	v_and_b32_e32 v23, 0xffff0000, v6
	v_lshlrev_b32_e32 v24, 16, v7
	v_and_b32_e32 v25, 0xffff0000, v7
	v_lshlrev_b32_e32 v18, 16, v8
	v_and_b32_e32 v19, 0xffff0000, v8
	v_lshlrev_b32_e32 v20, 16, v9
	v_and_b32_e32 v21, 0xffff0000, v9
	v_lshlrev_b32_e32 v14, 16, v10
	v_and_b32_e32 v15, 0xffff0000, v10
	v_lshlrev_b32_e32 v16, 16, v11
	v_and_b32_e32 v17, 0xffff0000, v11
	v_lshlrev_b32_e32 v10, 16, v12
	v_and_b32_e32 v11, 0xffff0000, v12
	v_lshlrev_b32_e32 v12, 16, v13
	v_and_b32_e32 v13, 0xffff0000, v13
	v_lshlrev_b32_e32 v6, 16, v2
	v_and_b32_e32 v7, 0xffff0000, v2
	v_lshlrev_b32_e32 v8, 16, v3
	v_and_b32_e32 v9, 0xffff0000, v3
	v_lshlrev_b32_e32 v2, 16, v4
	v_and_b32_e32 v3, 0xffff0000, v4
	v_lshlrev_b32_e32 v4, 16, v5
	v_and_b32_e32 v5, 0xffff0000, v5
	s_mov_b32 s42, 0
	v_lshl_add_u64 v[136:137], v[136:137], 0, s[22:23]
	v_lshl_add_u64 v[138:139], v[138:139], 0, s[22:23]
	s_barrier
	s_branch .LBB0_673

; #define PG8_STAGE(bufoff, gbase, voff) do { _Pragma("unroll") for (int _i = 0; _i < 2; ++_i) \
;     __builtin_amdgcn_global_load_lds((const unsigned*)((const char*)(gbase) + (voff)[_i]), (PG8_LAS unsigned*)(lds + (bufoff) + ldsw + _i * 8192), 16, 0, 0); } while (0)
; #define PG8_LDA(dst, b, h) do { _Pragma("unroll") for (int m = 0; m < 4; ++m) _Pragma("unroll") for (int k = 0; k < 2; ++k) dst[m][k] = *(const PG8_LAS bf16x8*)(lds + PG8_SA(b, h) + aoff + m * 2048 + k * 1024); } while (0)
; #define PG8_LDB(dst, b, h) do { _Pragma("unroll") for (int n = 0; n < 2; ++n) _Pragma("unroll") for (int k = 0; k < 2; ++k) dst[n][k] = *(const PG8_LAS bf16x8*)(lds + PG8_SB(b, h) + boff + n * 2048 + k * 1024); } while (0)
; #define PG8_MMA(ai, bj, At, Bt) do { __builtin_amdgcn_s_setprio(1); _Pragma("unroll") for (int m = 0; m < 4; ++m) _Pragma("unroll") for (int n = 0; n < 2; ++n) _Pragma("unroll") for (int k = 0; k < 2; ++k) \
;     acc[ai][bj][m][n] = __builtin_amdgcn_mfma_f32_16x16x32_bf16(Bt[n][k], At[m][k], acc[ai][bj][m][n], 0, 0, 0); __builtin_amdgcn_s_setprio(0); } while (0)
; #define PG8_WAIT_V(n) asm volatile("s_waitcnt vmcnt(" #n ")" ::: "memory")
; #define PG8_WAIT_L(n) asm volatile("s_waitcnt lgkmcnt(" #n ")" ::: "memory")
; #define PG8_BAR __builtin_amdgcn_s_barrier()
; #define PG8_SCHED __builtin_amdgcn_sched_barrier(0)
; template <class Epi>
; DI void gemm_phase(const bf16_t* __restrict__ gA, const bf16_t* __restrict__ gBt, int M, int N, int K, const Epi& E, char* lds_generic) {
;     ...
;       PG8_LDB(B0, 0, 0); PG8_SCHED; PG8_LDA(At, 0, 0); PG8_STAGE(PG8_SA(1, 1), a1 + hstep, voffA);
;       PG8_WAIT_L(8); PG8_BAR; PG8_WAIT_L(0); PG8_MMA(0, 0, At, B0); PG8_BAR; PG8_SCHED;
;       PG8_LDB(B1, 0, 1); PG8_STAGE(PG8_SB(0, 0), b2, voffB);
;       PG8_BAR; PG8_WAIT_L(0); PG8_MMA(0, 1, At, B1); PG8_BAR;
;       PG8_LDA(At, 0, 1); PG8_STAGE(PG8_SA(0, 0), a2, voffA);
;       PG8_BAR; PG8_WAIT_L(0); PG8_MMA(1, 0, At, B0); PG8_BAR; PG8_SCHED;
;       PG8_STAGE(PG8_SB(0, 1), b2 + hstep, voffB);
;       PG8_WAIT_V(6); PG8_BAR; PG8_MMA(1, 1, At, B1); PG8_BAR;
.LBB0_684:
	ds_read_b128 v[140:143], v146
	ds_read_b128 v[148:151], v146 offset:1024
	ds_read_b128 v[152:155], v146 offset:2048
	ds_read_b128 v[156:159], v146 offset:3072
	s_add_u32 s28, s88, 0x100
	s_addc_u32 s29, s89, 0
	s_cmp_eq_u32 s23, 40
	s_cselect_b32 s91, s87, s29
	s_cselect_b32 s90, s86, s28
	s_cselect_b32 s31, s1, s22
	s_cselect_b32 s30, s0, s21
	s_add_i32 m0, s12, 0xc000
	ds_read_b128 v[166:169], v145
	ds_read_b128 v[170:173], v145 offset:1024
	ds_read_b128 v[174:177], v145 offset:2048
	ds_read_b128 v[178:181], v145 offset:3072
	ds_read_b128 v[182:185], v145 offset:4096
	ds_read_b128 v[186:189], v145 offset:5120
	ds_read_b128 v[190:193], v145 offset:6144
	ds_read_b128 v[194:197], v145 offset:7168
	global_load_lds_dwordx4 v136, s[88:89]
	s_add_i32 m0, s12, 0xe000
	s_nop 0
	global_load_lds_dwordx4 v138, s[88:89]
	s_barrier
	s_waitcnt lgkmcnt(0)
	s_waitcnt lgkmcnt(0)
	v_mfma_f32_16x16x32_bf16 v[126:129], v[140:143], v[166:169], v[126:129]
	v_mfma_f32_16x16x32_bf16 v[122:125], v[152:155], v[166:169], v[122:125]
	v_mfma_f32_16x16x32_bf16 v[110:113], v[140:143], v[174:177], v[110:113]
	v_mfma_f32_16x16x32_bf16 v[106:109], v[152:155], v[174:177], v[106:109]
	v_mfma_f32_16x16x32_bf16 v[94:97], v[140:143], v[182:185], v[94:97]
	v_mfma_f32_16x16x32_bf16 v[90:93], v[152:155], v[182:185], v[90:93]
	v_mfma_f32_16x16x32_bf16 v[78:81], v[140:143], v[190:193], v[78:81]
	v_mfma_f32_16x16x32_bf16 v[74:77], v[152:155], v[190:193], v[74:77]
	v_mfma_f32_16x16x32_bf16 v[126:129], v[148:151], v[170:173], v[126:129]
	v_mfma_f32_16x16x32_bf16 v[122:125], v[156:159], v[170:173], v[122:125]
	v_mfma_f32_16x16x32_bf16 v[110:113], v[148:151], v[178:181], v[110:113]
	v_mfma_f32_16x16x32_bf16 v[106:109], v[156:159], v[178:181], v[106:109]
	v_mfma_f32_16x16x32_bf16 v[94:97], v[148:151], v[186:189], v[94:97]
	v_mfma_f32_16x16x32_bf16 v[90:93], v[156:159], v[186:189], v[90:93]
	v_mfma_f32_16x16x32_bf16 v[78:81], v[148:151], v[194:197], v[78:81]
	v_mfma_f32_16x16x32_bf16 v[74:77], v[156:159], v[194:197], v[74:77]
	s_barrier
	ds_read_b128 v[198:201], v146 offset:16384
	ds_read_b128 v[202:205], v146 offset:17408
	s_mov_b32 m0, s13
	ds_read_b128 v[206:209], v146 offset:18432
	ds_read_b128 v[210:213], v146 offset:19456
	global_load_lds_dwordx4 v0, s[30:31]
	s_mov_b32 m0, s14
	s_nop 0
	global_load_lds_dwordx4 v134, s[30:31]
	s_barrier
	s_waitcnt lgkmcnt(0)
	s_waitcnt lgkmcnt(0)
	v_mfma_f32_16x16x32_bf16 v[118:121], v[198:201], v[166:169], v[118:121]
	v_mfma_f32_16x16x32_bf16 v[114:117], v[206:209], v[166:169], v[114:117]
	v_mfma_f32_16x16x32_bf16 v[102:105], v[198:201], v[174:177], v[102:105]
	v_mfma_f32_16x16x32_bf16 v[98:101], v[206:209], v[174:177], v[98:101]
	v_mfma_f32_16x16x32_bf16 v[86:89], v[198:201], v[182:185], v[86:89]
	v_mfma_f32_16x16x32_bf16 v[82:85], v[206:209], v[182:185], v[82:85]
	v_mfma_f32_16x16x32_bf16 v[70:73], v[198:201], v[190:193], v[70:73]
	v_mfma_f32_16x16x32_bf16 v[66:69], v[206:209], v[190:193], v[66:69]
	v_mfma_f32_16x16x32_bf16 v[118:121], v[202:205], v[170:173], v[118:121]
	v_mfma_f32_16x16x32_bf16 v[114:117], v[210:213], v[170:173], v[114:117]
	v_mfma_f32_16x16x32_bf16 v[102:105], v[202:205], v[178:181], v[102:105]
	v_mfma_f32_16x16x32_bf16 v[98:101], v[210:213], v[178:181], v[98:101]
	v_mfma_f32_16x16x32_bf16 v[86:89], v[202:205], v[186:189], v[86:89]
	v_mfma_f32_16x16x32_bf16 v[82:85], v[210:213], v[186:189], v[82:85]
	v_mfma_f32_16x16x32_bf16 v[70:73], v[202:205], v[194:197], v[70:73]
	v_mfma_f32_16x16x32_bf16 v[66:69], v[210:213], v[194:197], v[66:69]
	s_mov_b32 m0, s12
	s_barrier
	ds_read_b128 v[166:169], v145 offset:16384
	ds_read_b128 v[170:173], v145 offset:17408
	ds_read_b128 v[174:177], v145 offset:18432
	ds_read_b128 v[178:181], v145 offset:19456
	ds_read_b128 v[182:185], v145 offset:20480
	ds_read_b128 v[186:189], v145 offset:21504
	ds_read_b128 v[190:193], v145 offset:22528
	ds_read_b128 v[194:197], v145 offset:23552
	global_load_lds_dwordx4 v130, s[90:91]
	s_mov_b32 m0, s15
	s_nop 0
	global_load_lds_dwordx4 v132, s[90:91]
	s_barrier
	s_waitcnt lgkmcnt(0)
	s_waitcnt lgkmcnt(0)
	v_mfma_f32_16x16x32_bf16 v[62:65], v[140:143], v[166:169], v[62:65]
	v_mfma_f32_16x16x32_bf16 v[58:61], v[152:155], v[166:169], v[58:61]
	v_mfma_f32_16x16x32_bf16 v[46:49], v[140:143], v[174:177], v[46:49]
	v_mfma_f32_16x16x32_bf16 v[42:45], v[152:155], v[174:177], v[42:45]
	v_mfma_f32_16x16x32_bf16 v[30:33], v[140:143], v[182:185], v[30:33]
	v_mfma_f32_16x16x32_bf16 v[26:29], v[152:155], v[182:185], v[26:29]
	v_mfma_f32_16x16x32_bf16 v[14:17], v[140:143], v[190:193], v[14:17]
	v_mfma_f32_16x16x32_bf16 v[10:13], v[152:155], v[190:193], v[10:13]
	v_mfma_f32_16x16x32_bf16 v[62:65], v[148:151], v[170:173], v[62:65]
	v_mfma_f32_16x16x32_bf16 v[58:61], v[156:159], v[170:173], v[58:61]
	v_mfma_f32_16x16x32_bf16 v[46:49], v[148:151], v[178:181], v[46:49]
	v_mfma_f32_16x16x32_bf16 v[42:45], v[156:159], v[178:181], v[42:45]
	v_mfma_f32_16x16x32_bf16 v[30:33], v[148:151], v[186:189], v[30:33]
	v_mfma_f32_16x16x32_bf16 v[26:29], v[156:159], v[186:189], v[26:29]
	v_mfma_f32_16x16x32_bf16 v[14:17], v[148:151], v[194:197], v[14:17]
	v_mfma_f32_16x16x32_bf16 v[10:13], v[156:159], v[194:197], v[10:13]
	s_barrier
	s_add_u32 s24, s30, 0xb0000
	s_addc_u32 s25, s31, 0
	s_mov_b32 m0, s18
	s_nop 0
	global_load_lds_dwordx4 v0, s[24:25]
	s_mov_b32 m0, s35
	s_nop 0
	global_load_lds_dwordx4 v134, s[24:25]
	s_waitcnt vmcnt(6)
	s_barrier
; #define PG8_STAGE(bufoff, gbase, voff) do { _Pragma("unroll") for (int _i = 0; _i < 2; ++_i) \
;     __builtin_amdgcn_global_load_lds((const unsigned*)((const char*)(gbase) + (voff)[_i]), (PG8_LAS unsigned*)(lds + (bufoff) + ldsw + _i * 8192), 16, 0, 0); } while (0)
; #define PG8_LDA(dst, b, h) do { _Pragma("unroll") for (int m = 0; m < 4; ++m) _Pragma("unroll") for (int k = 0; k < 2; ++k) dst[m][k] = *(const PG8_LAS bf16x8*)(lds + PG8_SA(b, h) + aoff + m * 2048 + k * 1024); } while (0)
; #define PG8_LDB(dst, b, h) do { _Pragma("unroll") for (int n = 0; n < 2; ++n) _Pragma("unroll") for (int k = 0; k < 2; ++k) dst[n][k] = *(const PG8_LAS bf16x8*)(lds + PG8_SB(b, h) + boff + n * 2048 + k * 1024); } while (0)
; #define PG8_MMA(ai, bj, At, Bt) do { __builtin_amdgcn_s_setprio(1); _Pragma("unroll") for (int m = 0; m < 4; ++m) _Pragma("unroll") for (int n = 0; n < 2; ++n) _Pragma("unroll") for (int k = 0; k < 2; ++k) \
;     acc[ai][bj][m][n] = __builtin_amdgcn_mfma_f32_16x16x32_bf16(Bt[n][k], At[m][k], acc[ai][bj][m][n], 0, 0, 0); __builtin_amdgcn_s_setprio(0); } while (0)
; #define PG8_WAIT_V(n) asm volatile("s_waitcnt vmcnt(" #n ")" ::: "memory")
; #define PG8_WAIT_L(n) asm volatile("s_waitcnt lgkmcnt(" #n ")" ::: "memory")
; #define PG8_BAR __builtin_amdgcn_s_barrier()
; #define PG8_SCHED __builtin_amdgcn_sched_barrier(0)
; template <class Epi>
; DI void gemm_phase(const bf16_t* __restrict__ gA, const bf16_t* __restrict__ gBt, int M, int N, int K, const Epi& E, char* lds_generic) {
;     ...
;       PG8_LDB(B0, 1, 0); PG8_SCHED; PG8_LDA(At, 1, 0); PG8_STAGE(PG8_SA(0, 1), a2 + hstep, voffA);
;       PG8_WAIT_L(8); PG8_BAR; PG8_WAIT_L(0); PG8_MMA(0, 0, At, B0); PG8_BAR; PG8_SCHED;
;       PG8_LDB(B1, 1, 1); PG8_STAGE(PG8_SB(1, 0), b3, voffB);
;       PG8_BAR; PG8_WAIT_L(0); PG8_MMA(0, 1, At, B1); PG8_BAR;
;       PG8_LDA(At, 1, 1); PG8_STAGE(PG8_SA(1, 0), a3, voffA);
;       PG8_BAR; PG8_WAIT_L(0); PG8_MMA(1, 0, At, B0); PG8_BAR; PG8_SCHED;
;       PG8_STAGE(PG8_SB(1, 1), b3 + hstep, voffB);
;       PG8_WAIT_V(6); PG8_BAR; PG8_MMA(1, 1, At, B1); PG8_BAR;
	v_mfma_f32_16x16x32_bf16 v[54:57], v[198:201], v[166:169], v[54:57]
	v_mfma_f32_16x16x32_bf16 v[50:53], v[206:209], v[166:169], v[50:53]
	v_mfma_f32_16x16x32_bf16 v[38:41], v[198:201], v[174:177], v[38:41]
	v_mfma_f32_16x16x32_bf16 v[34:37], v[206:209], v[174:177], v[34:37]
	v_mfma_f32_16x16x32_bf16 v[22:25], v[198:201], v[182:185], v[22:25]
	v_mfma_f32_16x16x32_bf16 v[18:21], v[206:209], v[182:185], v[18:21]
	v_mfma_f32_16x16x32_bf16 v[6:9], v[198:201], v[190:193], v[6:9]
	v_mfma_f32_16x16x32_bf16 v[2:5], v[206:209], v[190:193], v[2:5]
	v_mfma_f32_16x16x32_bf16 v[54:57], v[202:205], v[170:173], v[54:57]
	v_mfma_f32_16x16x32_bf16 v[50:53], v[210:213], v[170:173], v[50:53]
	v_mfma_f32_16x16x32_bf16 v[38:41], v[202:205], v[178:181], v[38:41]
	v_mfma_f32_16x16x32_bf16 v[34:37], v[210:213], v[178:181], v[34:37]
	v_mfma_f32_16x16x32_bf16 v[22:25], v[202:205], v[186:189], v[22:25]
	v_mfma_f32_16x16x32_bf16 v[18:21], v[210:213], v[186:189], v[18:21]
	v_mfma_f32_16x16x32_bf16 v[6:9], v[202:205], v[194:197], v[6:9]
	v_mfma_f32_16x16x32_bf16 v[2:5], v[210:213], v[194:197], v[2:5]
	s_barrier
	ds_read_b128 v[140:143], v146 offset:32768
	ds_read_b128 v[148:151], v146 offset:33792
	ds_read_b128 v[152:155], v146 offset:34816
	ds_read_b128 v[156:159], v146 offset:35840
	s_add_u32 s24, s90, 0xb0000
	s_addc_u32 s25, s91, 0
	s_mov_b32 m0, s53
	ds_read_b128 v[166:169], v145 offset:32768
	ds_read_b128 v[170:173], v145 offset:33792
	ds_read_b128 v[174:177], v145 offset:34816
	ds_read_b128 v[178:181], v145 offset:35840
	ds_read_b128 v[182:185], v145 offset:36864
	ds_read_b128 v[186:189], v145 offset:37888
	ds_read_b128 v[190:193], v145 offset:38912
	ds_read_b128 v[194:197], v145 offset:39936
	global_load_lds_dwordx4 v130, s[24:25]
	s_mov_b32 m0, s58
	s_nop 0
	global_load_lds_dwordx4 v132, s[24:25]
	s_barrier
	s_waitcnt lgkmcnt(0)
	s_waitcnt lgkmcnt(0)
	v_mfma_f32_16x16x32_bf16 v[126:129], v[140:143], v[166:169], v[126:129]
	v_mfma_f32_16x16x32_bf16 v[122:125], v[152:155], v[166:169], v[122:125]
	v_mfma_f32_16x16x32_bf16 v[110:113], v[140:143], v[174:177], v[110:113]
	v_mfma_f32_16x16x32_bf16 v[106:109], v[152:155], v[174:177], v[106:109]
	v_mfma_f32_16x16x32_bf16 v[94:97], v[140:143], v[182:185], v[94:97]
	v_mfma_f32_16x16x32_bf16 v[90:93], v[152:155], v[182:185], v[90:93]
	v_mfma_f32_16x16x32_bf16 v[78:81], v[140:143], v[190:193], v[78:81]
	v_mfma_f32_16x16x32_bf16 v[74:77], v[152:155], v[190:193], v[74:77]
	v_mfma_f32_16x16x32_bf16 v[126:129], v[148:151], v[170:173], v[126:129]
	v_mfma_f32_16x16x32_bf16 v[122:125], v[156:159], v[170:173], v[122:125]
	v_mfma_f32_16x16x32_bf16 v[110:113], v[148:151], v[178:181], v[110:113]
	v_mfma_f32_16x16x32_bf16 v[106:109], v[156:159], v[178:181], v[106:109]
	v_mfma_f32_16x16x32_bf16 v[94:97], v[148:151], v[186:189], v[94:97]
	v_mfma_f32_16x16x32_bf16 v[90:93], v[156:159], v[186:189], v[90:93]
	v_mfma_f32_16x16x32_bf16 v[78:81], v[148:151], v[194:197], v[78:81]
	v_mfma_f32_16x16x32_bf16 v[74:77], v[156:159], v[194:197], v[74:77]
	s_barrier
	s_mov_b32 m0, s59
	ds_read_b128 v[198:201], v146 offset:49152
	ds_read_b128 v[202:205], v146 offset:50176
	ds_read_b128 v[206:209], v146 offset:51200
	ds_read_b128 v[210:213], v146 offset:52224
	s_add_u32 s24, s30, 0x80
	s_addc_u32 s25, s31, 0
	global_load_lds_dwordx4 v0, s[24:25]
	s_mov_b32 m0, s60
	s_nop 0
	s_add_u32 s24, s30, 0x80
	s_addc_u32 s25, s31, 0
	global_load_lds_dwordx4 v134, s[24:25]
	s_barrier
	s_waitcnt lgkmcnt(0)
	s_waitcnt lgkmcnt(0)
	v_mfma_f32_16x16x32_bf16 v[118:121], v[198:201], v[166:169], v[118:121]
	v_mfma_f32_16x16x32_bf16 v[114:117], v[206:209], v[166:169], v[114:117]
	v_mfma_f32_16x16x32_bf16 v[102:105], v[198:201], v[174:177], v[102:105]
	v_mfma_f32_16x16x32_bf16 v[98:101], v[206:209], v[174:177], v[98:101]
	v_mfma_f32_16x16x32_bf16 v[86:89], v[198:201], v[182:185], v[86:89]
	v_mfma_f32_16x16x32_bf16 v[82:85], v[206:209], v[182:185], v[82:85]
	v_mfma_f32_16x16x32_bf16 v[70:73], v[198:201], v[190:193], v[70:73]
	v_mfma_f32_16x16x32_bf16 v[66:69], v[206:209], v[190:193], v[66:69]
	v_mfma_f32_16x16x32_bf16 v[118:121], v[202:205], v[170:173], v[118:121]
	v_mfma_f32_16x16x32_bf16 v[114:117], v[210:213], v[170:173], v[114:117]
	v_mfma_f32_16x16x32_bf16 v[102:105], v[202:205], v[178:181], v[102:105]
	v_mfma_f32_16x16x32_bf16 v[98:101], v[210:213], v[178:181], v[98:101]
	v_mfma_f32_16x16x32_bf16 v[86:89], v[202:205], v[186:189], v[86:89]
	v_mfma_f32_16x16x32_bf16 v[82:85], v[210:213], v[186:189], v[82:85]
	v_mfma_f32_16x16x32_bf16 v[70:73], v[202:205], v[194:197], v[70:73]
	v_mfma_f32_16x16x32_bf16 v[66:69], v[210:213], v[194:197], v[66:69]
	s_mov_b32 m0, s62
	s_barrier
	ds_read_b128 v[166:169], v145 offset:49152
	ds_read_b128 v[170:173], v145 offset:50176
	ds_read_b128 v[174:177], v145 offset:51200
	ds_read_b128 v[178:181], v145 offset:52224
	ds_read_b128 v[182:185], v145 offset:53248
	ds_read_b128 v[186:189], v145 offset:54272
	ds_read_b128 v[190:193], v145 offset:55296
	ds_read_b128 v[194:197], v145 offset:56320
	s_add_u32 s24, s90, 0x80
	s_addc_u32 s25, s91, 0
	global_load_lds_dwordx4 v130, s[24:25]
	s_mov_b32 m0, s72
	s_nop 0
	s_add_u32 s24, s90, 0x80
	s_addc_u32 s25, s91, 0
	global_load_lds_dwordx4 v132, s[24:25]
	s_barrier
; DI bf16_t f2bf(float x) { unsigned u = __float_as_uint(x); u += 0x7fffu + ((u >> 16) & 1u); return (bf16_t)(u >> 16); }
; DI unsigned pack2(float lo, float hi) { f32x2_t v = {lo, hi}; return __builtin_bit_cast(unsigned, __builtin_convertvector(v, bf16x2_t)); }
; #define PG8_LAS __attribute__((address_space(3)))
; #define PG8_STAGE(bufoff, gbase, voff) do { _Pragma("unroll") for (int _i = 0; _i < 2; ++_i) \
;     __builtin_amdgcn_global_load_lds((const unsigned*)((const char*)(gbase) + (voff)[_i]), (PG8_LAS unsigned*)(lds + (bufoff) + ldsw + _i * 8192), 16, 0, 0); } while (0)
; #define PG8_MMA(ai, bj, At, Bt) do { __builtin_amdgcn_s_setprio(1); _Pragma("unroll") for (int m = 0; m < 4; ++m) _Pragma("unroll") for (int n = 0; n < 2; ++n) _Pragma("unroll") for (int k = 0; k < 2; ++k) \
;     acc[ai][bj][m][n] = __builtin_amdgcn_mfma_f32_16x16x32_bf16(Bt[n][k], At[m][k], acc[ai][bj][m][n], 0, 0, 0); __builtin_amdgcn_s_setprio(0); } while (0)
; #define PG8_BAR __builtin_amdgcn_s_barrier()
;   DI void operator()(const f32x4 (&acc)[2][2][4][2], const Unit& u, int wr, int wc, int fr, int fq, const PG8_LAS float*) const {
;     const int row0 = u.pm * BM + wr * 64 + fr, col0 = u.pn * BM + wc * 32 + 8 * fq;
; #pragma unroll
;     for (int ai = 0; ai < 2; ++ai)
; #pragma unroll
;       for (int m = 0; m < 4; ++m) { const int row = row0 + ai * HALF + m * 16; bf16_t* rowp = dst + (size_t)row * DM + col0; float ss = 0.f;
; #pragma unroll
;         for (int bj = 0; bj < 2; ++bj) { const f32x4 v0 = acc[ai][bj][m][0] * coef, v1 = acc[ai][bj][m][1] * coef;
;           ss += v0[0] * v0[0] + v0[1] * v0[1] + v0[2] * v0[2] + v0[3] * v0[3] + v1[0] * v1[0] + v1[1] * v1[1] + v1[2] * v1[2] + v1[3] * v1[3];
;           u32x4 w; w.x = pack2(v0[0], v0[1]); w.y = pack2(v0[2], v0[3]); w.z = pack2(v1[0], v1[1]); w.w = pack2(v1[2], v1[3]);
;           *(u32x4*)(rowp + bj * HALF) = w; }
;         ss += __shfl_xor(ss, 16); ss += __shfl_xor(ss, 32);
;         if (fq == 0) ssq[(size_t)row * 16 + u.pn * 4 + wc] = f2bf(ss); }
; template <class Epi>
; DI void gemm_phase(const bf16_t* __restrict__ gA, const bf16_t* __restrict__ gBt, int M, int N, int K, const Epi& E, char* lds_generic) {
;     ...
;       PG8_BAR; PG8_WAIT_L(0); PG8_MMA(1, 0, At, B0); PG8_BAR; PG8_SCHED;
;       PG8_STAGE(PG8_SB(1, 1), b3 + hstep, voffB);
;       PG8_WAIT_V(6); PG8_BAR; PG8_MMA(1, 1, At, B1); PG8_BAR;
	s_waitcnt lgkmcnt(0)
	s_waitcnt lgkmcnt(0)
	v_mfma_f32_16x16x32_bf16 v[62:65], v[140:143], v[166:169], v[62:65]
	v_mfma_f32_16x16x32_bf16 v[58:61], v[152:155], v[166:169], v[58:61]
	v_mfma_f32_16x16x32_bf16 v[46:49], v[140:143], v[174:177], v[46:49]
	v_mfma_f32_16x16x32_bf16 v[42:45], v[152:155], v[174:177], v[42:45]
	v_mfma_f32_16x16x32_bf16 v[30:33], v[140:143], v[182:185], v[30:33]
	v_mfma_f32_16x16x32_bf16 v[26:29], v[152:155], v[182:185], v[26:29]
	v_mfma_f32_16x16x32_bf16 v[14:17], v[140:143], v[190:193], v[14:17]
	v_mfma_f32_16x16x32_bf16 v[10:13], v[152:155], v[190:193], v[10:13]
	v_mfma_f32_16x16x32_bf16 v[62:65], v[148:151], v[170:173], v[62:65]
	v_mfma_f32_16x16x32_bf16 v[58:61], v[156:159], v[170:173], v[58:61]
	v_mfma_f32_16x16x32_bf16 v[46:49], v[148:151], v[178:181], v[46:49]
	v_mfma_f32_16x16x32_bf16 v[42:45], v[156:159], v[178:181], v[42:45]
	v_mfma_f32_16x16x32_bf16 v[30:33], v[148:151], v[186:189], v[30:33]
	v_mfma_f32_16x16x32_bf16 v[26:29], v[156:159], v[186:189], v[26:29]
	v_mfma_f32_16x16x32_bf16 v[14:17], v[148:151], v[194:197], v[14:17]
	v_mfma_f32_16x16x32_bf16 v[10:13], v[156:159], v[194:197], v[10:13]
	s_barrier
	s_add_u32 s24, s30, 0xb0080
	s_addc_u32 s25, s31, 0
	s_mov_b32 m0, s74
	s_nop 0
	global_load_lds_dwordx4 v0, s[24:25]
	s_mov_b32 m0, s19
	s_nop 0
	global_load_lds_dwordx4 v134, s[24:25]
	s_waitcnt vmcnt(6)
	s_barrier
	v_mfma_f32_16x16x32_bf16 v[54:57], v[198:201], v[166:169], v[54:57]
	v_mfma_f32_16x16x32_bf16 v[50:53], v[206:209], v[166:169], v[50:53]
	v_mfma_f32_16x16x32_bf16 v[38:41], v[198:201], v[174:177], v[38:41]
	v_mfma_f32_16x16x32_bf16 v[34:37], v[206:209], v[174:177], v[34:37]
	v_mfma_f32_16x16x32_bf16 v[22:25], v[198:201], v[182:185], v[22:25]
	v_mfma_f32_16x16x32_bf16 v[18:21], v[206:209], v[182:185], v[18:21]
	v_mfma_f32_16x16x32_bf16 v[6:9], v[198:201], v[190:193], v[6:9]
	v_mfma_f32_16x16x32_bf16 v[2:5], v[206:209], v[190:193], v[2:5]
	v_mfma_f32_16x16x32_bf16 v[54:57], v[202:205], v[170:173], v[54:57]
	v_mfma_f32_16x16x32_bf16 v[50:53], v[210:213], v[170:173], v[50:53]
	v_mfma_f32_16x16x32_bf16 v[38:41], v[202:205], v[178:181], v[38:41]
	v_mfma_f32_16x16x32_bf16 v[34:37], v[210:213], v[178:181], v[34:37]
	v_mfma_f32_16x16x32_bf16 v[22:25], v[202:205], v[186:189], v[22:25]
	v_mfma_f32_16x16x32_bf16 v[18:21], v[210:213], v[186:189], v[18:21]
	v_mfma_f32_16x16x32_bf16 v[6:9], v[202:205], v[194:197], v[6:9]
	v_mfma_f32_16x16x32_bf16 v[2:5], v[210:213], v[194:197], v[2:5]
	s_add_i32 s23, s23, 2
	s_add_u32 s21, s21, 0x100
	s_addc_u32 s22, s22, 0
	s_cmp_gt_u32 s23, 41
	s_mov_b64 s[88:89], s[28:29]
	s_barrier
	s_cbranch_scc0 .LBB0_684
	v_pk_mul_f32 v[126:127], v[126:127], 0.5 op_sel_hi:[1,0]
	v_pk_mul_f32 v[128:129], v[128:129], 0.5 op_sel_hi:[1,0]
	v_mul_f32_e32 v154, v127, v127
	v_fmac_f32_e32 v154, v126, v126
	v_fmac_f32_e32 v154, v128, v128
	v_pk_mul_f32 v[118:119], v[118:119], 0.5 op_sel_hi:[1,0]
	v_pk_mul_f32 v[152:153], v[124:125], 0.5 op_sel_hi:[1,0]
	v_pk_mul_f32 v[124:125], v[122:123], 0.5 op_sel_hi:[1,0]
	v_fmac_f32_e32 v154, v129, v129
	v_cvt_pk_bf16_f32 v123, v128, v129
	v_pk_mul_f32 v[128:129], v[114:115], 0.5 op_sel_hi:[1,0]
	v_mul_f32_e32 v114, v119, v119
	v_pk_mul_f32 v[120:121], v[120:121], 0.5 op_sel_hi:[1,0]
	v_fmac_f32_e32 v114, v118, v118
	v_fmac_f32_e32 v114, v120, v120
	v_fmac_f32_e32 v114, v121, v121
	v_fmac_f32_e32 v154, v124, v124
	v_fmac_f32_e32 v114, v128, v128
	v_xor_b32_e32 v143, 16, v223
	v_fmac_f32_e32 v154, v125, v125
	v_cvt_pk_bf16_f32 v122, v126, v127
	v_pk_mul_f32 v[126:127], v[116:117], 0.5 op_sel_hi:[1,0]
	v_fmac_f32_e32 v114, v129, v129
	v_cmp_lt_i32_e32 vcc, v143, v225
	v_fmac_f32_e32 v154, v152, v152
	v_fmac_f32_e32 v114, v126, v126
	v_cndmask_b32_e32 v143, v223, v143, vcc
	v_fmac_f32_e32 v154, v153, v153
	v_fmac_f32_e32 v114, v127, v127
	v_lshlrev_b32_e32 v149, 2, v143
	v_add_f32_e32 v114, v154, v114
	ds_bpermute_b32 v115, v149, v114
	v_xor_b32_e32 v143, 32, v223
	v_cmp_lt_i32_e32 vcc, v143, v225
	v_lshl_add_u32 v142, s9, 8, v144
	v_lshl_or_b32 v140, s76, 8, v147
	v_cndmask_b32_e32 v143, v223, v143, vcc
	v_lshlrev_b32_e32 v148, 2, v143
	s_waitcnt lgkmcnt(0)
	v_add_f32_e32 v114, v114, v115
	ds_bpermute_b32 v115, v148, v114
	v_ashrrev_i32_e32 v143, 31, v142
	v_lshlrev_b64 v[150:151], 11, v[142:143]
	v_ashrrev_i32_e32 v141, 31, v140
	s_lshl_b32 s28, s76, 2
	v_lshl_add_u64 v[150:151], s[26:27], 0, v[150:151]
	s_ashr_i32 s29, s28, 31
	v_lshl_add_u64 v[150:151], v[140:141], 1, v[150:151]
	v_cvt_pk_bf16_f32 v124, v124, v125
	v_cvt_pk_bf16_f32 v125, v152, v153
	v_cvt_pk_bf16_f32 v116, v118, v119
	v_cvt_pk_bf16_f32 v117, v120, v121
	v_cvt_pk_bf16_f32 v118, v128, v129
	v_cvt_pk_bf16_f32 v119, v126, v127
	global_store_dwordx4 v[150:151], v[122:125], off
	global_store_dwordx4 v[150:151], v[116:119], off offset:256
	s_and_saveexec_b64 s[30:31], s[36:37]
	s_cbranch_execz .LBB0_687
	s_waitcnt lgkmcnt(0)
	v_add_f32_e32 v114, v114, v115
	v_bfe_u32 v115, v114, 16, 1
	v_add3_u32 v116, v114, v115, s63
	v_lshlrev_b64 v[114:115], 5, v[142:143]
	v_lshl_add_u64 v[114:115], s[84:85], 0, v[114:115]
	v_lshl_add_u64 v[114:115], s[28:29], 1, v[114:115]
	s_lshl_b32 s76, s7, 1
	v_lshl_add_u64 v[114:115], v[114:115], 0, s[76:77]
	global_store_short_d16_hi v[114:115], v116, off
